# attention loops: counted lgkmcnt waits at the first consumer of each K / V fragment instead of lgkmcnt(0) after the read burst
# baseline (speedup 1.0000x reference)
.LBB0_934:
	s_or_b64 exec, exec, s[8:9]
	v_add3_u32 v64, s18, v190, v168
	ds_read_b128 v[32:35], v64
	ds_read_b128 v[36:39], v64 offset:0x1a00
	ds_read_b128 v[40:43], v64 offset:32
	ds_read_b128 v[44:47], v64 offset:0x1a20
	ds_read_b128 v[136:139], v64 offset:64
	ds_read_b128 v[140:143], v64 offset:0x1a40
	ds_read_b128 v[144:147], v64 offset:96
	ds_read_b128 v[148:151], v64 offset:0x1a60
	ds_read_b128 v[152:155], v64 offset:128
	ds_read_b128 v[156:159], v64 offset:0x1a80
	ds_read_b128 v[206:209], v64 offset:160
	ds_read_b128 v[160:163], v64 offset:0x1aa0
	s_nop 0
	s_waitcnt lgkmcnt(11)
	v_mfma_f32_32x32x16_bf16 v[80:95], v[32:35], v[116:119], v[48:63]
	v_add_u32_e32 v32, s18, v191
	v_add3_u32 v32, v32, v189, s87
	s_waitcnt lgkmcnt(10)
	v_mfma_f32_32x32x16_bf16 v[64:79], v[36:39], v[116:119], v[48:63]
	s_waitcnt lgkmcnt(9)
	v_mfma_f32_32x32x16_bf16 v[80:95], v[40:43], v[112:115], v[80:95]
	s_waitcnt lgkmcnt(8)
	v_mfma_f32_32x32x16_bf16 v[64:79], v[44:47], v[112:115], v[64:79]
	s_waitcnt lgkmcnt(7)
	v_mfma_f32_32x32x16_bf16 v[80:95], v[136:139], v[108:111], v[80:95]
	s_waitcnt lgkmcnt(6)
	v_mfma_f32_32x32x16_bf16 v[64:79], v[140:143], v[108:111], v[64:79]
	s_waitcnt lgkmcnt(5)
	v_mfma_f32_32x32x16_bf16 v[80:95], v[144:147], v[104:107], v[80:95]
	s_waitcnt lgkmcnt(4)
	v_mfma_f32_32x32x16_bf16 v[64:79], v[148:151], v[104:107], v[64:79]
	s_waitcnt lgkmcnt(3)
	v_mfma_f32_32x32x16_bf16 v[80:95], v[152:155], v[100:103], v[80:95]
	s_waitcnt lgkmcnt(2)
	v_mfma_f32_32x32x16_bf16 v[64:79], v[156:159], v[100:103], v[64:79]
	s_waitcnt lgkmcnt(0)
	v_mfma_f32_32x32x16_bf16 v[64:79], v[160:163], v[96:99], v[64:79]
	ds_read_b64 v[164:165], v32
	ds_read_b64 v[166:167], v32 offset:16
	ds_read_b64 v[160:161], v32 offset:32
	ds_read_b64 v[162:163], v32 offset:48
	ds_read_b64 v[156:157], v32 offset:64
	ds_read_b64 v[158:159], v32 offset:80
	ds_read_b64 v[152:153], v32 offset:96
	ds_read_b64 v[154:155], v32 offset:112
	ds_read_b64 v[148:149], v32 offset:0x1100
	ds_read_b64 v[150:151], v32 offset:0x1110
	ds_read_b64 v[144:145], v32 offset:0x1120
	ds_read_b64 v[146:147], v32 offset:0x1130
	ds_read_b64 v[140:141], v32 offset:0x1140
	ds_read_b64 v[142:143], v32 offset:0x1150
	ds_read_b64 v[136:137], v32 offset:0x1160
	ds_read_b64 v[138:139], v32 offset:0x1170
	v_mfma_f32_32x32x16_bf16 v[80:95], v[206:209], v[96:99], v[80:95]
	s_nop 11
	v_max_f32_e32 v32, v80, v64
	v_max_f32_e32 v33, v81, v65
	v_max_f32_e32 v34, v83, v67
	v_max3_f32 v34, v82, v66, v34
	v_max3_f32 v32, v32, v33, v34
	v_max_f32_e32 v33, v85, v69
	v_max_f32_e32 v34, v87, v71
	v_max3_f32 v33, v84, v68, v33
	v_max3_f32 v34, v86, v70, v34
	v_max3_f32 v32, v32, v33, v34
	v_max_f32_e32 v33, v89, v73
	v_max_f32_e32 v34, v91, v75
	v_max3_f32 v33, v88, v72, v33
	v_max3_f32 v34, v90, v74, v34
	v_max3_f32 v32, v32, v33, v34
	v_max_f32_e32 v33, v93, v77
	v_max_f32_e32 v35, v95, v95
	v_max_f32_e32 v34, v35, v79
	v_max3_f32 v33, v92, v76, v33
	v_max3_f32 v34, v94, v78, v34
	v_max3_f32 v32, v32, v33, v34
	v_mov_b32_e32 v33, v32
	s_nop 1
	v_permlane32_swap_b32_e32 v32, v33
	v_max_f32_e32 v32, v32, v33
	v_cmp_lt_f32_e32 vcc, s80, v32
	s_cbranch_vccz .LBB0_936
	v_max_f32_e32 v48, 0, v32
	v_exp_f32_e64 v32, -v48
	s_nop 0
	v_mov_b32_e32 v49, v32
	v_pk_mul_f32 v[30:31], v[30:31], v[32:33] op_sel_hi:[1,0]
	v_pk_mul_f32 v[28:29], v[28:29], v[32:33] op_sel_hi:[1,0]
	v_pk_mul_f32 v[26:27], v[26:27], v[32:33] op_sel_hi:[1,0]
	v_pk_mul_f32 v[24:25], v[24:25], v[32:33] op_sel_hi:[1,0]
	v_pk_mul_f32 v[22:23], v[22:23], v[32:33] op_sel_hi:[1,0]
	v_pk_mul_f32 v[20:21], v[20:21], v[32:33] op_sel_hi:[1,0]
	v_pk_mul_f32 v[18:19], v[18:19], v[32:33] op_sel_hi:[1,0]
	v_pk_mul_f32 v[14:15], v[14:15], v[32:33] op_sel_hi:[1,0]
	v_pk_mul_f32 v[12:13], v[12:13], v[32:33] op_sel_hi:[1,0]
	v_pk_mul_f32 v[10:11], v[10:11], v[32:33] op_sel_hi:[1,0]
	v_pk_mul_f32 v[8:9], v[8:9], v[32:33] op_sel_hi:[1,0]
	v_pk_mul_f32 v[6:7], v[6:7], v[32:33] op_sel_hi:[1,0]
	v_pk_mul_f32 v[4:5], v[4:5], v[32:33] op_sel_hi:[1,0]
	v_pk_mul_f32 v[2:3], v[2:3], v[32:33] op_sel_hi:[1,0]
	v_pk_mul_f32 v[16:17], v[16:17], v[32:33] op_sel_hi:[1,0]
	v_pk_mul_f32 v[0:1], v[0:1], v[32:33] op_sel_hi:[1,0]
	v_pk_add_f32 v[178:179], v[176:177], v[48:49]
	v_pk_mul_f32 v[32:33], v[176:177], v[48:49]
	v_pk_add_f32 v[80:81], v[80:81], v[48:49] op_sel_hi:[1,0] neg_lo:[0,1] neg_hi:[0,1]
	v_mov_b32_e32 v179, v33
	v_pk_add_f32 v[32:33], v[178:179], 0 neg_lo:[1,1] neg_hi:[1,1]
	v_pk_add_f32 v[64:65], v[64:65], v[48:49] op_sel_hi:[1,0] neg_lo:[0,1] neg_hi:[0,1]
	v_pk_add_f32 v[82:83], v[82:83], v[48:49] op_sel_hi:[1,0] neg_lo:[0,1] neg_hi:[0,1]
	v_pk_add_f32 v[66:67], v[66:67], v[48:49] op_sel_hi:[1,0] neg_lo:[0,1] neg_hi:[0,1]
	v_pk_add_f32 v[84:85], v[84:85], v[48:49] op_sel_hi:[1,0] neg_lo:[0,1] neg_hi:[0,1]
	v_pk_add_f32 v[68:69], v[68:69], v[48:49] op_sel_hi:[1,0] neg_lo:[0,1] neg_hi:[0,1]
	v_pk_add_f32 v[86:87], v[86:87], v[48:49] op_sel_hi:[1,0] neg_lo:[0,1] neg_hi:[0,1]
	v_pk_add_f32 v[70:71], v[70:71], v[48:49] op_sel_hi:[1,0] neg_lo:[0,1] neg_hi:[0,1]
	v_pk_add_f32 v[88:89], v[88:89], v[48:49] op_sel_hi:[1,0] neg_lo:[0,1] neg_hi:[0,1]
	v_pk_add_f32 v[72:73], v[72:73], v[48:49] op_sel_hi:[1,0] neg_lo:[0,1] neg_hi:[0,1]
	v_pk_add_f32 v[90:91], v[90:91], v[48:49] op_sel_hi:[1,0] neg_lo:[0,1] neg_hi:[0,1]
	v_pk_add_f32 v[74:75], v[74:75], v[48:49] op_sel_hi:[1,0] neg_lo:[0,1] neg_hi:[0,1]
	v_pk_add_f32 v[92:93], v[92:93], v[48:49] op_sel_hi:[1,0] neg_lo:[0,1] neg_hi:[0,1]
	v_pk_add_f32 v[76:77], v[76:77], v[48:49] op_sel_hi:[1,0] neg_lo:[0,1] neg_hi:[0,1]
	v_mov_b32_e32 v33, v32
	v_mov_b32_e32 v34, v32
	v_mov_b32_e32 v35, v32
	v_mov_b32_e32 v36, v32
	v_mov_b32_e32 v37, v32
	v_mov_b32_e32 v38, v32
	v_mov_b32_e32 v39, v32
	v_mov_b32_e32 v40, v32
	v_mov_b32_e32 v41, v32
	v_mov_b32_e32 v42, v32
	v_mov_b32_e32 v43, v32
	v_mov_b32_e32 v44, v32
	v_mov_b32_e32 v45, v32
	v_mov_b32_e32 v46, v32
	v_mov_b32_e32 v47, v32
	v_pk_add_f32 v[94:95], v[94:95], v[48:49] op_sel_hi:[1,0] neg_lo:[0,1] neg_hi:[0,1]
	v_pk_add_f32 v[78:79], v[78:79], v[48:49] op_sel_hi:[1,0] neg_lo:[0,1] neg_hi:[0,1]
	v_mov_b32_e32 v48, v32
	v_mov_b32_e32 v49, v32
	v_mov_b32_e32 v50, v32
	v_mov_b32_e32 v51, v32
	v_mov_b32_e32 v52, v32
	v_mov_b32_e32 v53, v32
	v_mov_b32_e32 v54, v32
	v_mov_b32_e32 v55, v32
	v_mov_b32_e32 v56, v32
	v_mov_b32_e32 v57, v32
	v_mov_b32_e32 v58, v32
	v_mov_b32_e32 v59, v32
	v_mov_b32_e32 v60, v32
	v_mov_b32_e32 v61, v32
	v_mov_b32_e32 v62, v32
	v_mov_b32_e32 v63, v32
	v_mov_b32_e32 v176, v178
	s_branch .LBB0_937

.LBB0_943:
	s_or_b64 exec, exec, s[2:3]
	v_add_u32_e32 v48, 0x8000, v192
	s_waitcnt lgkmcnt(0)
	s_barrier
	ds_read_b128 v[64:67], v48
	ds_read_b128 v[68:71], v48 offset:0x1a00
	ds_read_b128 v[72:75], v48 offset:32
	ds_read_b128 v[76:79], v48 offset:0x1a20
	ds_read_b128 v[80:83], v48 offset:64
	ds_read_b128 v[84:87], v48 offset:0x1a40
	ds_read_b128 v[88:91], v48 offset:96
	ds_read_b128 v[92:95], v48 offset:0x1a60
	ds_read_b128 v[120:123], v48 offset:128
	ds_read_b128 v[124:127], v48 offset:0x1a80
	ds_read_b128 v[128:131], v48 offset:160
	ds_read_b128 v[132:135], v48 offset:0x1aa0
	s_nop 0
	s_waitcnt lgkmcnt(11)
	v_mfma_f32_32x32x16_bf16 v[48:63], v[64:67], v[116:119], v[32:47]
	s_waitcnt lgkmcnt(10)
	v_mfma_f32_32x32x16_bf16 v[32:47], v[68:71], v[116:119], v[32:47]
	s_waitcnt lgkmcnt(9)
	v_mfma_f32_32x32x16_bf16 v[48:63], v[72:75], v[112:115], v[48:63]
	s_waitcnt lgkmcnt(8)
	v_mfma_f32_32x32x16_bf16 v[32:47], v[76:79], v[112:115], v[32:47]
	s_waitcnt lgkmcnt(7)
	v_mfma_f32_32x32x16_bf16 v[48:63], v[80:83], v[108:111], v[48:63]
	s_waitcnt lgkmcnt(6)
	v_mfma_f32_32x32x16_bf16 v[32:47], v[84:87], v[108:111], v[32:47]
	s_waitcnt lgkmcnt(5)
	v_mfma_f32_32x32x16_bf16 v[48:63], v[88:91], v[104:107], v[48:63]
	s_waitcnt lgkmcnt(4)
	v_mfma_f32_32x32x16_bf16 v[32:47], v[92:95], v[104:107], v[32:47]
	s_waitcnt lgkmcnt(3)
	v_mfma_f32_32x32x16_bf16 v[48:63], v[120:123], v[100:103], v[48:63]
	s_waitcnt lgkmcnt(2)
	v_mfma_f32_32x32x16_bf16 v[32:47], v[124:127], v[100:103], v[32:47]
	v_add_u32_e32 v100, 0xb400, v204
	ds_read_b64 v[92:93], v100
	ds_read_b64 v[94:95], v100 offset:16
	ds_read_b64 v[88:89], v100 offset:32
	ds_read_b64 v[90:91], v100 offset:48
	ds_read_b64 v[84:85], v100 offset:64
	ds_read_b64 v[86:87], v100 offset:80
	ds_read_b64 v[80:81], v100 offset:96
	ds_read_b64 v[82:83], v100 offset:112
	ds_read_b64 v[76:77], v100 offset:0x1100
	ds_read_b64 v[78:79], v100 offset:0x1110
	ds_read_b64 v[72:73], v100 offset:0x1120
	ds_read_b64 v[74:75], v100 offset:0x1130
	ds_read_b64 v[68:69], v100 offset:0x1140
	ds_read_b64 v[70:71], v100 offset:0x1150
	ds_read_b64 v[64:65], v100 offset:0x1160
	ds_read_b64 v[66:67], v100 offset:0x1170
	s_waitcnt lgkmcnt(15)
	v_mfma_f32_32x32x16_bf16 v[32:47], v[132:135], v[96:99], v[32:47]
	v_mfma_f32_32x32x16_bf16 v[48:63], v[128:131], v[96:99], v[48:63]
	s_nop 10
	v_max_f32_e32 v100, v32, v32
	v_max_f32_e32 v97, v49, v33
	v_max_f32_e32 v98, v51, v35
	v_max_f32_e32 v96, v48, v100
	v_max3_f32 v98, v50, v34, v98
	v_max3_f32 v96, v96, v97, v98
	v_max_f32_e32 v97, v53, v37
	v_max_f32_e32 v98, v55, v39
	v_max3_f32 v97, v52, v36, v97
	v_max3_f32 v98, v54, v38, v98
	v_max3_f32 v96, v96, v97, v98
	v_max_f32_e32 v97, v57, v41
	v_max_f32_e32 v98, v59, v43
	v_max3_f32 v97, v56, v40, v97
	v_max3_f32 v98, v58, v42, v98
	v_max3_f32 v96, v96, v97, v98
	v_max_f32_e32 v97, v61, v45
	v_max_f32_e32 v99, v63, v63
	v_max_f32_e32 v98, v99, v47
	v_max3_f32 v97, v60, v44, v97
	v_max3_f32 v98, v62, v46, v98
	v_max3_f32 v96, v96, v97, v98
	v_mov_b32_e32 v97, v96
	s_nop 1
	v_permlane32_swap_b32_e32 v96, v97
	v_max_f32_e32 v96, v96, v97
	v_cmp_lt_f32_e32 vcc, s80, v96
	s_cbranch_vccz .LBB0_945
	v_max_f32_e32 v96, 0, v96
	v_exp_f32_e64 v98, -v96
	v_pk_add_f32 v[48:49], v[48:49], v[96:97] op_sel_hi:[1,0] neg_lo:[0,1] neg_hi:[0,1]
	v_pk_add_f32 v[32:33], v[32:33], v[96:97] op_sel_hi:[1,0] neg_lo:[0,1] neg_hi:[0,1]
	v_pk_add_f32 v[50:51], v[50:51], v[96:97] op_sel_hi:[1,0] neg_lo:[0,1] neg_hi:[0,1]
	v_pk_mul_f32 v[14:15], v[14:15], v[98:99] op_sel_hi:[1,0]
	v_pk_mul_f32 v[12:13], v[12:13], v[98:99] op_sel_hi:[1,0]
	v_pk_mul_f32 v[10:11], v[10:11], v[98:99] op_sel_hi:[1,0]
	v_pk_mul_f32 v[8:9], v[8:9], v[98:99] op_sel_hi:[1,0]
	v_pk_mul_f32 v[6:7], v[6:7], v[98:99] op_sel_hi:[1,0]
	v_pk_mul_f32 v[4:5], v[4:5], v[98:99] op_sel_hi:[1,0]
	v_pk_mul_f32 v[2:3], v[2:3], v[98:99] op_sel_hi:[1,0]
	v_pk_mul_f32 v[0:1], v[0:1], v[98:99] op_sel_hi:[1,0]
	v_pk_mul_f32 v[30:31], v[30:31], v[98:99] op_sel_hi:[1,0]
	v_pk_mul_f32 v[28:29], v[28:29], v[98:99] op_sel_hi:[1,0]
	v_pk_mul_f32 v[26:27], v[26:27], v[98:99] op_sel_hi:[1,0]
	v_pk_mul_f32 v[24:25], v[24:25], v[98:99] op_sel_hi:[1,0]
	v_pk_mul_f32 v[22:23], v[22:23], v[98:99] op_sel_hi:[1,0]
	v_pk_mul_f32 v[20:21], v[20:21], v[98:99] op_sel_hi:[1,0]
	v_pk_mul_f32 v[18:19], v[18:19], v[98:99] op_sel_hi:[1,0]
	v_pk_mul_f32 v[16:17], v[16:17], v[98:99] op_sel_hi:[1,0]
	v_mul_f32_e32 v136, v136, v98
	v_pk_add_f32 v[34:35], v[34:35], v[96:97] op_sel_hi:[1,0] neg_lo:[0,1] neg_hi:[0,1]
	v_pk_add_f32 v[52:53], v[52:53], v[96:97] op_sel_hi:[1,0] neg_lo:[0,1] neg_hi:[0,1]
	v_pk_add_f32 v[36:37], v[36:37], v[96:97] op_sel_hi:[1,0] neg_lo:[0,1] neg_hi:[0,1]
	v_pk_add_f32 v[54:55], v[54:55], v[96:97] op_sel_hi:[1,0] neg_lo:[0,1] neg_hi:[0,1]
	v_pk_add_f32 v[38:39], v[38:39], v[96:97] op_sel_hi:[1,0] neg_lo:[0,1] neg_hi:[0,1]
	v_pk_add_f32 v[56:57], v[56:57], v[96:97] op_sel_hi:[1,0] neg_lo:[0,1] neg_hi:[0,1]
	v_pk_add_f32 v[40:41], v[40:41], v[96:97] op_sel_hi:[1,0] neg_lo:[0,1] neg_hi:[0,1]
	v_pk_add_f32 v[58:59], v[58:59], v[96:97] op_sel_hi:[1,0] neg_lo:[0,1] neg_hi:[0,1]
	v_pk_add_f32 v[42:43], v[42:43], v[96:97] op_sel_hi:[1,0] neg_lo:[0,1] neg_hi:[0,1]
	v_pk_add_f32 v[60:61], v[60:61], v[96:97] op_sel_hi:[1,0] neg_lo:[0,1] neg_hi:[0,1]
	v_pk_add_f32 v[44:45], v[44:45], v[96:97] op_sel_hi:[1,0] neg_lo:[0,1] neg_hi:[0,1]
	v_pk_add_f32 v[62:63], v[62:63], v[96:97] op_sel_hi:[1,0] neg_lo:[0,1] neg_hi:[0,1]
	v_pk_add_f32 v[46:47], v[46:47], v[96:97] op_sel_hi:[1,0] neg_lo:[0,1] neg_hi:[0,1]

.LBB0_959:
	s_or_b64 exec, exec, s[0:1]
	v_lshl_add_u64 v[64:65], s[4:5], 0, v[206:207]
	v_add_co_u32_e32 v64, vcc, 0xa808000, v64
	v_add3_u32 v96, s29, v245, v204
	s_nop 0
	v_addc_co_u32_e32 v65, vcc, 0, v65, vcc
	global_load_dwordx4 v[152:155], v[64:65], off
	global_load_dwordx4 v[156:159], v[64:65], off offset:256
	ds_read_b128 v[64:67], v96
	ds_read_b128 v[68:71], v96 offset:0x1200
	ds_read_b128 v[72:75], v96 offset:32
	ds_read_b128 v[76:79], v96 offset:0x1220
	ds_read_b128 v[160:163], v96 offset:64
	ds_read_b128 v[164:167], v96 offset:0x1240
	ds_read_b128 v[168:171], v96 offset:96
	ds_read_b128 v[172:175], v96 offset:0x1260
	s_nop 0
	s_waitcnt lgkmcnt(7)
	v_mfma_f32_32x32x16_bf16 v[112:127], v[64:67], v[140:143], v[80:95]
	v_add_u32_e32 v64, s29, v246
	v_add3_u32 v247, v64, v244, s87
	s_waitcnt lgkmcnt(6)
	v_mfma_f32_32x32x16_bf16 v[96:111], v[68:71], v[140:143], v[80:95]
	s_waitcnt lgkmcnt(5)
	v_mfma_f32_32x32x16_bf16 v[112:127], v[72:75], v[136:139], v[112:127]
	s_waitcnt lgkmcnt(4)
	v_mfma_f32_32x32x16_bf16 v[96:111], v[76:79], v[136:139], v[96:111]
	s_waitcnt lgkmcnt(3)
	v_mfma_f32_32x32x16_bf16 v[112:127], v[160:163], v[132:135], v[112:127]
	s_waitcnt lgkmcnt(2)
	v_mfma_f32_32x32x16_bf16 v[96:111], v[164:167], v[132:135], v[96:111]
	s_waitcnt lgkmcnt(1)
	v_mfma_f32_32x32x16_bf16 v[112:127], v[168:171], v[128:131], v[112:127]
	s_waitcnt lgkmcnt(0)
	v_mfma_f32_32x32x16_bf16 v[96:111], v[172:175], v[128:131], v[96:111]
	s_nop 10
	ds_read_b64 v[188:189], v247
	ds_read_b64 v[190:191], v247 offset:16
	ds_read_b64 v[184:185], v247 offset:32
	ds_read_b64 v[186:187], v247 offset:48
	ds_read_b64 v[180:181], v247 offset:64
	ds_read_b64 v[182:183], v247 offset:80
	ds_read_b64 v[176:177], v247 offset:96
	ds_read_b64 v[178:179], v247 offset:112
	ds_read_b64 v[172:173], v247 offset:0x1100
	ds_read_b64 v[174:175], v247 offset:0x1110
	ds_read_b64 v[168:169], v247 offset:0x1120
	ds_read_b64 v[170:171], v247 offset:0x1130
	ds_read_b64 v[164:165], v247 offset:0x1140
	ds_read_b64 v[166:167], v247 offset:0x1150
	ds_read_b64 v[160:161], v247 offset:0x1160
	ds_read_b64 v[162:163], v247 offset:0x1170
	v_max_f32_e32 v64, v112, v96
	v_max_f32_e32 v65, v113, v97
	v_max_f32_e32 v66, v115, v99
	v_max3_f32 v66, v114, v98, v66
	v_max3_f32 v64, v64, v65, v66
	v_max_f32_e32 v65, v117, v101
	v_max_f32_e32 v66, v119, v103
	v_max3_f32 v65, v116, v100, v65
	v_max3_f32 v66, v118, v102, v66
	v_max3_f32 v64, v64, v65, v66
	v_max_f32_e32 v65, v121, v105
	v_max_f32_e32 v66, v123, v107
	v_max3_f32 v65, v120, v104, v65
	v_max3_f32 v66, v122, v106, v66
	v_max3_f32 v64, v64, v65, v66
	v_max_f32_e32 v65, v125, v109
	v_max_f32_e32 v67, v127, v127
	v_max_f32_e32 v66, v67, v111
	v_max3_f32 v65, v124, v108, v65
	v_max3_f32 v66, v126, v110, v66
	v_max3_f32 v64, v64, v65, v66
	v_mov_b32_e32 v65, v64
	s_nop 1
	v_permlane32_swap_b32_e32 v64, v65
	v_max_f32_e32 v64, v64, v65
	v_cmp_lt_f32_e32 vcc, s80, v64
	s_cbranch_vccz .LBB0_961
	v_max_f32_e32 v80, 0, v64
	v_exp_f32_e64 v64, -v80
	s_nop 0
	v_mov_b32_e32 v81, v64
	v_pk_mul_f32 v[14:15], v[14:15], v[64:65] op_sel_hi:[1,0]
	v_pk_mul_f32 v[12:13], v[12:13], v[64:65] op_sel_hi:[1,0]
	v_pk_mul_f32 v[10:11], v[10:11], v[64:65] op_sel_hi:[1,0]
	v_pk_mul_f32 v[8:9], v[8:9], v[64:65] op_sel_hi:[1,0]
	v_pk_mul_f32 v[6:7], v[6:7], v[64:65] op_sel_hi:[1,0]
	v_pk_mul_f32 v[4:5], v[4:5], v[64:65] op_sel_hi:[1,0]
	v_pk_mul_f32 v[2:3], v[2:3], v[64:65] op_sel_hi:[1,0]
	v_pk_mul_f32 v[0:1], v[0:1], v[64:65] op_sel_hi:[1,0]
	v_pk_mul_f32 v[30:31], v[30:31], v[64:65] op_sel_hi:[1,0]
	v_pk_mul_f32 v[28:29], v[28:29], v[64:65] op_sel_hi:[1,0]
	v_pk_mul_f32 v[26:27], v[26:27], v[64:65] op_sel_hi:[1,0]
	v_pk_mul_f32 v[24:25], v[24:25], v[64:65] op_sel_hi:[1,0]
	v_pk_mul_f32 v[22:23], v[22:23], v[64:65] op_sel_hi:[1,0]
	v_pk_mul_f32 v[20:21], v[20:21], v[64:65] op_sel_hi:[1,0]
	v_pk_mul_f32 v[18:19], v[18:19], v[64:65] op_sel_hi:[1,0]
	v_pk_mul_f32 v[16:17], v[16:17], v[64:65] op_sel_hi:[1,0]
	v_pk_mul_f32 v[62:63], v[62:63], v[64:65] op_sel_hi:[1,0]
	v_pk_mul_f32 v[60:61], v[60:61], v[64:65] op_sel_hi:[1,0]
	v_pk_mul_f32 v[58:59], v[58:59], v[64:65] op_sel_hi:[1,0]
	v_pk_mul_f32 v[56:57], v[56:57], v[64:65] op_sel_hi:[1,0]
	v_pk_mul_f32 v[54:55], v[54:55], v[64:65] op_sel_hi:[1,0]
	v_pk_mul_f32 v[52:53], v[52:53], v[64:65] op_sel_hi:[1,0]
	v_pk_mul_f32 v[50:51], v[50:51], v[64:65] op_sel_hi:[1,0]
	v_pk_mul_f32 v[48:49], v[48:49], v[64:65] op_sel_hi:[1,0]
	v_pk_mul_f32 v[46:47], v[46:47], v[64:65] op_sel_hi:[1,0]
	v_pk_mul_f32 v[44:45], v[44:45], v[64:65] op_sel_hi:[1,0]
	v_pk_mul_f32 v[42:43], v[42:43], v[64:65] op_sel_hi:[1,0]
	v_pk_mul_f32 v[40:41], v[40:41], v[64:65] op_sel_hi:[1,0]
	v_pk_mul_f32 v[38:39], v[38:39], v[64:65] op_sel_hi:[1,0]
	v_pk_mul_f32 v[36:37], v[36:37], v[64:65] op_sel_hi:[1,0]
	v_pk_mul_f32 v[34:35], v[34:35], v[64:65] op_sel_hi:[1,0]
	v_pk_mul_f32 v[32:33], v[32:33], v[64:65] op_sel_hi:[1,0]
	v_pk_add_f32 v[214:215], v[212:213], v[80:81]
	v_pk_mul_f32 v[64:65], v[212:213], v[80:81]
	v_pk_add_f32 v[112:113], v[112:113], v[80:81] op_sel_hi:[1,0] neg_lo:[0,1] neg_hi:[0,1]
	v_mov_b32_e32 v215, v65
	v_pk_add_f32 v[64:65], v[214:215], 0 neg_lo:[1,1] neg_hi:[1,1]
	v_pk_add_f32 v[96:97], v[96:97], v[80:81] op_sel_hi:[1,0] neg_lo:[0,1] neg_hi:[0,1]
	v_pk_add_f32 v[114:115], v[114:115], v[80:81] op_sel_hi:[1,0] neg_lo:[0,1] neg_hi:[0,1]
	v_pk_add_f32 v[98:99], v[98:99], v[80:81] op_sel_hi:[1,0] neg_lo:[0,1] neg_hi:[0,1]
	v_pk_add_f32 v[116:117], v[116:117], v[80:81] op_sel_hi:[1,0] neg_lo:[0,1] neg_hi:[0,1]
	v_pk_add_f32 v[100:101], v[100:101], v[80:81] op_sel_hi:[1,0] neg_lo:[0,1] neg_hi:[0,1]
	v_pk_add_f32 v[118:119], v[118:119], v[80:81] op_sel_hi:[1,0] neg_lo:[0,1] neg_hi:[0,1]
	v_pk_add_f32 v[102:103], v[102:103], v[80:81] op_sel_hi:[1,0] neg_lo:[0,1] neg_hi:[0,1]
	v_pk_add_f32 v[120:121], v[120:121], v[80:81] op_sel_hi:[1,0] neg_lo:[0,1] neg_hi:[0,1]
	v_pk_add_f32 v[104:105], v[104:105], v[80:81] op_sel_hi:[1,0] neg_lo:[0,1] neg_hi:[0,1]
	v_pk_add_f32 v[122:123], v[122:123], v[80:81] op_sel_hi:[1,0] neg_lo:[0,1] neg_hi:[0,1]
	v_pk_add_f32 v[106:107], v[106:107], v[80:81] op_sel_hi:[1,0] neg_lo:[0,1] neg_hi:[0,1]
	v_pk_add_f32 v[124:125], v[124:125], v[80:81] op_sel_hi:[1,0] neg_lo:[0,1] neg_hi:[0,1]
	v_pk_add_f32 v[108:109], v[108:109], v[80:81] op_sel_hi:[1,0] neg_lo:[0,1] neg_hi:[0,1]
	v_mov_b32_e32 v65, v64
	v_mov_b32_e32 v66, v64
	v_mov_b32_e32 v67, v64
	v_mov_b32_e32 v68, v64
	v_mov_b32_e32 v69, v64
	v_mov_b32_e32 v70, v64
	v_mov_b32_e32 v71, v64
	v_mov_b32_e32 v72, v64
	v_mov_b32_e32 v73, v64
	v_mov_b32_e32 v74, v64
	v_mov_b32_e32 v75, v64
	v_mov_b32_e32 v76, v64
	v_mov_b32_e32 v77, v64
	v_mov_b32_e32 v78, v64
	v_mov_b32_e32 v79, v64
	v_pk_add_f32 v[126:127], v[126:127], v[80:81] op_sel_hi:[1,0] neg_lo:[0,1] neg_hi:[0,1]
	v_pk_add_f32 v[110:111], v[110:111], v[80:81] op_sel_hi:[1,0] neg_lo:[0,1] neg_hi:[0,1]
	v_mov_b32_e32 v80, v64
	v_mov_b32_e32 v81, v64
	v_mov_b32_e32 v82, v64
	v_mov_b32_e32 v83, v64
	v_mov_b32_e32 v84, v64
	v_mov_b32_e32 v85, v64
	v_mov_b32_e32 v86, v64
	v_mov_b32_e32 v87, v64
	v_mov_b32_e32 v88, v64
	v_mov_b32_e32 v89, v64
	v_mov_b32_e32 v90, v64
	v_mov_b32_e32 v91, v64
	v_mov_b32_e32 v92, v64
	v_mov_b32_e32 v93, v64
	v_mov_b32_e32 v94, v64
	v_mov_b32_e32 v95, v64
	v_mov_b32_e32 v212, v214
	s_branch .LBB0_962

.LBB0_962:
	v_exp_f32_e32 v232, v112
	v_exp_f32_e32 v233, v113
	v_exp_f32_e32 v96, v96
	v_exp_f32_e32 v97, v97
	v_exp_f32_e32 v114, v114
	v_exp_f32_e32 v115, v115
	v_exp_f32_e32 v98, v98
	v_exp_f32_e32 v99, v99
	v_pk_add_f32 v[112:113], v[232:233], 0 op_sel_hi:[1,0]
	v_exp_f32_e32 v116, v116
	v_exp_f32_e32 v117, v117
	v_pk_add_f32 v[112:113], v[96:97], v[112:113]
	v_exp_f32_e32 v100, v100
	v_exp_f32_e32 v101, v101
	v_pk_add_f32 v[112:113], v[114:115], v[112:113]
	v_exp_f32_e32 v118, v118
	v_exp_f32_e32 v119, v119
	v_pk_add_f32 v[112:113], v[98:99], v[112:113]
	v_exp_f32_e32 v102, v102
	v_exp_f32_e32 v103, v103
	v_pk_add_f32 v[112:113], v[116:117], v[112:113]
	v_exp_f32_e32 v120, v120
	v_exp_f32_e32 v121, v121
	v_pk_add_f32 v[112:113], v[100:101], v[112:113]
	v_exp_f32_e32 v248, v104
	v_exp_f32_e32 v249, v105
	v_pk_add_f32 v[112:113], v[118:119], v[112:113]
	v_exp_f32_e32 v122, v122
	v_exp_f32_e32 v123, v123
	v_pk_add_f32 v[112:113], v[102:103], v[112:113]
	v_exp_f32_e32 v250, v106
	v_exp_f32_e32 v251, v107
	v_pk_add_f32 v[104:105], v[120:121], v[112:113]
	v_exp_f32_e32 v106, v124
	v_exp_f32_e32 v107, v125
	v_exp_f32_e32 v124, v108
	v_exp_f32_e32 v125, v109
	v_exp_f32_e32 v252, v110
	v_exp_f32_e32 v253, v111
	v_cvt_pk_bf16_f32 v108, v232, v233
	v_cvt_pk_bf16_f32 v109, v114, v115
	v_cvt_pk_bf16_f32 v110, v116, v117
	v_cvt_pk_bf16_f32 v111, v118, v119
	v_pk_add_f32 v[104:105], v[248:249], v[104:105]
	s_waitcnt lgkmcnt(0)
	v_exp_f32_e32 v126, v126
	v_mfma_f32_32x32x16_bf16 v[0:15], v[188:191], v[108:111], v[0:15]
	v_add_f32_e64 v104, v122, v104
	v_add_f32_e64 v105, v123, v105
	v_exp_f32_e32 v127, v127
	v_pk_add_f32 v[104:105], v[250:251], v[104:105]
	v_cvt_pk_bf16_f32 v96, v96, v97
	v_pk_add_f32 v[104:105], v[106:107], v[104:105]
	v_cvt_pk_bf16_f32 v106, v106, v107
	v_pk_add_f32 v[104:105], v[124:125], v[104:105]
	v_mfma_f32_32x32x16_bf16 v[16:31], v[172:175], v[108:111], v[16:31]
	v_add_f32_e64 v104, v126, v104
	v_add_f32_e64 v105, v127, v105
	v_cvt_pk_bf16_f32 v107, v126, v127
	v_add_f32_e64 v104, v252, v104
	v_add_f32_e64 v105, v253, v105
	v_cvt_pk_bf16_f32 v97, v98, v99
	v_pk_add_f32 v[112:113], v[104:105], v[104:105] op_sel:[0,1] op_sel_hi:[1,0]
	v_cvt_pk_bf16_f32 v104, v120, v121
	v_cvt_pk_bf16_f32 v105, v122, v123
	v_cvt_pk_bf16_f32 v98, v100, v101
	v_cvt_pk_bf16_f32 v99, v102, v103
	v_mfma_f32_32x32x16_bf16 v[0:15], v[184:187], v[104:107], v[0:15]
	v_cvt_pk_bf16_f32 v100, v248, v249
	v_cvt_pk_bf16_f32 v101, v250, v251
	v_cvt_pk_bf16_f32 v102, v124, v125
	v_cvt_pk_bf16_f32 v103, v252, v253
	v_add_u32_e32 v126, 0x2200, v247
	s_add_i32 s28, s28, 0x8000
	v_lshl_add_u64 v[206:207], v[206:207], 0, s[70:71]
	v_mfma_f32_32x32x16_bf16 v[16:31], v[168:171], v[104:107], v[16:31]
	v_lshl_add_u64 v[208:209], v[208:209], 0, s[94:95]
	v_lshl_add_u64 v[210:211], v[210:211], 0, s[94:95]
	s_cmp_lg_u32 s28, 0x118000
	v_mfma_f32_32x32x16_bf16 v[0:15], v[180:183], v[96:99], v[0:15]
	v_mfma_f32_32x32x16_bf16 v[16:31], v[164:167], v[96:99], v[16:31]
	v_mfma_f32_32x32x16_bf16 v[0:15], v[176:179], v[100:103], v[0:15]
	v_mfma_f32_32x32x16_bf16 v[16:31], v[160:163], v[100:103], v[16:31]
	ds_read_b64 v[176:177], v126
	ds_read_b64 v[178:179], v126 offset:16
	ds_read_b64 v[172:173], v126 offset:32
	ds_read_b64 v[174:175], v126 offset:48
	ds_read_b64 v[168:169], v126 offset:64
	ds_read_b64 v[170:171], v126 offset:80
	ds_read_b64 v[164:165], v126 offset:96
	ds_read_b64 v[166:167], v126 offset:112
	ds_read_b64 v[160:161], v126 offset:0x1100
	ds_read_b64 v[162:163], v126 offset:0x1110
	ds_read_b64 v[122:123], v126 offset:0x1120
	ds_read_b64 v[124:125], v126 offset:0x1130
	ds_read_b64 v[118:119], v126 offset:0x1140
	ds_read_b64 v[120:121], v126 offset:0x1150
	ds_read_b64 v[114:115], v126 offset:0x1160
	ds_read_b64 v[116:117], v126 offset:0x1170
	s_nop 0
	s_nop 0
	s_waitcnt lgkmcnt(14)
	v_mfma_f32_32x32x16_bf16 v[48:63], v[176:179], v[108:111], v[48:63]
	s_waitcnt lgkmcnt(6)
	v_mfma_f32_32x32x16_bf16 v[32:47], v[160:163], v[108:111], v[32:47]
	v_add_f32_e64 v160, v215, v112
	v_add_f32_e64 v161, v214, v113
	v_mfma_f32_32x32x16_bf16 v[48:63], v[172:175], v[104:107], v[48:63]
	s_waitcnt lgkmcnt(4)
	v_mfma_f32_32x32x16_bf16 v[32:47], v[122:125], v[104:107], v[32:47]
	v_mfma_f32_32x32x16_bf16 v[48:63], v[168:171], v[96:99], v[48:63]
	s_waitcnt lgkmcnt(2)
	v_mfma_f32_32x32x16_bf16 v[32:47], v[118:121], v[96:99], v[32:47]
	v_mfma_f32_32x32x16_bf16 v[48:63], v[164:167], v[100:103], v[48:63]
	s_waitcnt lgkmcnt(0)
	v_mfma_f32_32x32x16_bf16 v[32:47], v[114:117], v[100:103], v[32:47]
	s_cbranch_scc0 .LBB0_964
	v_mov_b32_e32 v213, v160
	s_branch .LBB0_955
.LBB0_964:
	v_mov_b64_e32 v[64:65], v[80:81]
	v_mov_b64_e32 v[66:67], v[82:83]
	v_mov_b64_e32 v[68:69], v[84:85]
	v_mov_b64_e32 v[70:71], v[86:87]
	v_mov_b64_e32 v[72:73], v[88:89]
	v_mov_b64_e32 v[74:75], v[90:91]
	v_mov_b64_e32 v[76:77], v[92:93]
	v_mov_b64_e32 v[78:79], v[94:95]
	s_waitcnt vmcnt(2)
	ds_write_b128 v222, v[148:151] offset:32768
	s_and_saveexec_b64 s[0:1], s[2:3]
	ds_write_b128 v192, v[144:147] offset:32768
	s_or_b64 exec, exec, s[0:1]
	s_waitcnt vmcnt(0)
	v_perm_b32 v80, v156, v152, s85
	v_perm_b32 v81, v156, v152, s86
	v_add_u32_e32 v82, 0xb400, v223
	ds_write2_b32 v82, v80, v81 offset1:34
	v_perm_b32 v80, v157, v153, s85
	v_perm_b32 v81, v157, v153, s86
	ds_write2_b32 v82, v80, v81 offset0:68 offset1:102
	v_perm_b32 v80, v158, v154, s85
	v_perm_b32 v81, v158, v154, s86
	ds_write2_b32 v82, v80, v81 offset0:136 offset1:170
	v_perm_b32 v80, v159, v155, s85
	v_perm_b32 v81, v159, v155, s86
	ds_write2_b32 v82, v80, v81 offset0:204 offset1:238
	v_add_u32_e32 v80, 0x8000, v242
	s_waitcnt lgkmcnt(0)
	s_barrier
	ds_read_b128 v[96:99], v80
	ds_read_b128 v[100:103], v80 offset:0x1200
	ds_read_b128 v[104:107], v80 offset:32
	ds_read_b128 v[108:111], v80 offset:0x1220
	ds_read_b128 v[112:115], v80 offset:64
	ds_read_b128 v[116:119], v80 offset:0x1240
	ds_read_b128 v[144:147], v80 offset:96
	ds_read_b128 v[120:123], v80 offset:0x1260
	s_nop 0
	s_waitcnt lgkmcnt(7)
	v_mfma_f32_32x32x16_bf16 v[80:95], v[96:99], v[140:143], v[64:79]
	s_waitcnt lgkmcnt(6)
	v_mfma_f32_32x32x16_bf16 v[64:79], v[100:103], v[140:143], v[64:79]
	s_waitcnt lgkmcnt(5)
	v_mfma_f32_32x32x16_bf16 v[80:95], v[104:107], v[136:139], v[80:95]
	s_waitcnt lgkmcnt(4)
	v_mfma_f32_32x32x16_bf16 v[64:79], v[108:111], v[136:139], v[64:79]
	s_waitcnt lgkmcnt(3)
	v_mfma_f32_32x32x16_bf16 v[80:95], v[112:115], v[132:135], v[80:95]
	s_waitcnt lgkmcnt(2)
	v_mfma_f32_32x32x16_bf16 v[64:79], v[116:119], v[132:135], v[64:79]
	v_add_u32_e32 v132, 0xb400, v243
	s_waitcnt lgkmcnt(0)
	v_mfma_f32_32x32x16_bf16 v[64:79], v[120:123], v[128:131], v[64:79]
	ds_read_b64 v[124:125], v132
	ds_read_b64 v[126:127], v132 offset:16
	ds_read_b64 v[120:121], v132 offset:32
	ds_read_b64 v[122:123], v132 offset:48
	ds_read_b64 v[116:117], v132 offset:64
	ds_read_b64 v[118:119], v132 offset:80
	ds_read_b64 v[112:113], v132 offset:96
	ds_read_b64 v[114:115], v132 offset:112
	ds_read_b64 v[108:109], v132 offset:0x1100
	ds_read_b64 v[110:111], v132 offset:0x1110
	ds_read_b64 v[104:105], v132 offset:0x1120
	ds_read_b64 v[106:107], v132 offset:0x1130
	ds_read_b64 v[100:101], v132 offset:0x1140
	ds_read_b64 v[102:103], v132 offset:0x1150
	ds_read_b64 v[96:97], v132 offset:0x1160
	ds_read_b64 v[98:99], v132 offset:0x1170
	v_mfma_f32_32x32x16_bf16 v[80:95], v[144:147], v[128:131], v[80:95]
	s_nop 10
	v_max_f32_e32 v133, v64, v64
	v_max_f32_e32 v129, v81, v65
	v_max_f32_e32 v130, v83, v67
	v_max_f32_e32 v128, v80, v133
	v_max3_f32 v130, v82, v66, v130
	v_max3_f32 v128, v128, v129, v130
	v_max_f32_e32 v129, v85, v69
	v_max_f32_e32 v130, v87, v71
	v_max3_f32 v129, v84, v68, v129
	v_max3_f32 v130, v86, v70, v130
	v_max3_f32 v128, v128, v129, v130
	v_max_f32_e32 v129, v89, v73
	v_max_f32_e32 v130, v91, v75
	v_max3_f32 v129, v88, v72, v129
	v_max3_f32 v130, v90, v74, v130
	v_max3_f32 v128, v128, v129, v130
	v_max_f32_e32 v129, v93, v77
	v_max_f32_e32 v131, v95, v95
	v_max_f32_e32 v130, v131, v79
	v_max3_f32 v129, v92, v76, v129
	v_max3_f32 v130, v94, v78, v130
	v_max3_f32 v128, v128, v129, v130
	v_mov_b32_e32 v129, v128
	s_nop 1
	v_permlane32_swap_b32_e32 v128, v129
	v_max_f32_e32 v128, v128, v129
	v_cmp_lt_f32_e32 vcc, s80, v128
	s_cbranch_vccz .LBB0_968
	v_max_f32_e32 v128, 0, v128
	v_exp_f32_e64 v130, -v128
	v_pk_add_f32 v[80:81], v[80:81], v[128:129] op_sel_hi:[1,0] neg_lo:[0,1] neg_hi:[0,1]
	v_pk_add_f32 v[64:65], v[64:65], v[128:129] op_sel_hi:[1,0] neg_lo:[0,1] neg_hi:[0,1]
	v_pk_add_f32 v[82:83], v[82:83], v[128:129] op_sel_hi:[1,0] neg_lo:[0,1] neg_hi:[0,1]
	v_pk_mul_f32 v[14:15], v[14:15], v[130:131] op_sel_hi:[1,0]
	v_pk_mul_f32 v[12:13], v[12:13], v[130:131] op_sel_hi:[1,0]
	v_pk_mul_f32 v[10:11], v[10:11], v[130:131] op_sel_hi:[1,0]
	v_pk_mul_f32 v[8:9], v[8:9], v[130:131] op_sel_hi:[1,0]
	v_pk_mul_f32 v[6:7], v[6:7], v[130:131] op_sel_hi:[1,0]
	v_pk_mul_f32 v[4:5], v[4:5], v[130:131] op_sel_hi:[1,0]
	v_pk_mul_f32 v[2:3], v[2:3], v[130:131] op_sel_hi:[1,0]
	v_pk_mul_f32 v[0:1], v[0:1], v[130:131] op_sel_hi:[1,0]
	v_pk_mul_f32 v[30:31], v[30:31], v[130:131] op_sel_hi:[1,0]
	v_pk_mul_f32 v[28:29], v[28:29], v[130:131] op_sel_hi:[1,0]
	v_pk_mul_f32 v[26:27], v[26:27], v[130:131] op_sel_hi:[1,0]
	v_pk_mul_f32 v[24:25], v[24:25], v[130:131] op_sel_hi:[1,0]
	v_pk_mul_f32 v[22:23], v[22:23], v[130:131] op_sel_hi:[1,0]
	v_pk_mul_f32 v[20:21], v[20:21], v[130:131] op_sel_hi:[1,0]
	v_pk_mul_f32 v[18:19], v[18:19], v[130:131] op_sel_hi:[1,0]
	v_pk_mul_f32 v[16:17], v[16:17], v[130:131] op_sel_hi:[1,0]
	v_pk_mul_f32 v[62:63], v[62:63], v[130:131] op_sel_hi:[1,0]
	v_pk_mul_f32 v[60:61], v[60:61], v[130:131] op_sel_hi:[1,0]
	v_pk_mul_f32 v[58:59], v[58:59], v[130:131] op_sel_hi:[1,0]
	v_pk_mul_f32 v[56:57], v[56:57], v[130:131] op_sel_hi:[1,0]
	v_pk_mul_f32 v[54:55], v[54:55], v[130:131] op_sel_hi:[1,0]
	v_pk_mul_f32 v[52:53], v[52:53], v[130:131] op_sel_hi:[1,0]
	v_pk_mul_f32 v[50:51], v[50:51], v[130:131] op_sel_hi:[1,0]
	v_pk_mul_f32 v[48:49], v[48:49], v[130:131] op_sel_hi:[1,0]
	v_pk_mul_f32 v[46:47], v[46:47], v[130:131] op_sel_hi:[1,0]
	v_pk_mul_f32 v[44:45], v[44:45], v[130:131] op_sel_hi:[1,0]
	v_pk_mul_f32 v[42:43], v[42:43], v[130:131] op_sel_hi:[1,0]
	v_pk_mul_f32 v[40:41], v[40:41], v[130:131] op_sel_hi:[1,0]
; #define LAS __attribute__((address_space(3)))
; #define otid() ((wv << 6) | olane())
; template <int DK, int DV, int VAR>
; __device__ __forceinline__ void attn_pass(LAS unsigned char* lds, const bf16_t* Qg, const bf16_t* Kg, const bf16_t* Vg, int ntiles, float cs, f32x16 (&O)[DV / 32], float& lsum, int wv) {
;     ...
;     lsum = xsum32(lrun);
;     ...
; }
; template <int VAR> __device__ __forceinline__ void attn_unit_a(LAS unsigned char* lds, KP p, int l, int bh, int qb, int wv) {
;     unsigned char* ws = p->ws;
;     const int b = bh >> 2, h = bh & 3;
;     const int tid_ = otid(); const int lane = tid_ & 63, wid = tid_ >> 6, l32 = lane & 31, hf = lane >> 5;
;     const int ntiles = qb == 0 ? CTX / 64 : TK / 64;
;     const int q0 = qb == 0 ? 0 : CTX + (qb - 1) * 256;
;     const bf16_t* QA = (const bf16_t*)(ws + WS_QA); const bf16_t* KA = (const bf16_t*)(ws + WS_KA); const bf16_t* VA = (const bf16_t*)(ws + WS_VA);
;     const float cs = 0.125f * 1.4426950408889634f;
;     const float lam = ((const float*)(ws + WS_LAM))[l];
;     const float lam_init = ((const float*)(ws + WS_LAM))[8 + l];
;     f32x16 O[4]; float lsum;
;     const bf16_t* Vg = VA + (size_t)(b * 4 + h) * TK * 128;
;     attn_pass<64, 128, VAR>(lds, QA + ((size_t)(b * 8 + h * 2 + 0) * TK + q0) * 64, KA + (size_t)(b * 8 + h * 2 + 0) * TK * 64, Vg, ntiles, cs, O, lsum, wv);
;     LAS unsigned* o0 = (LAS unsigned*)(lds + 65536 + wid * 8192) + lane;
;     { const float inv = 1.f / lsum;
	v_pk_mul_f32 v[38:39], v[38:39], v[130:131] op_sel_hi:[1,0]
	v_pk_mul_f32 v[36:37], v[36:37], v[130:131] op_sel_hi:[1,0]
	v_pk_mul_f32 v[34:35], v[34:35], v[130:131] op_sel_hi:[1,0]
	v_pk_mul_f32 v[32:33], v[32:33], v[130:131] op_sel_hi:[1,0]
	v_mul_f32_e32 v160, v160, v130
	v_pk_add_f32 v[66:67], v[66:67], v[128:129] op_sel_hi:[1,0] neg_lo:[0,1] neg_hi:[0,1]
	v_pk_add_f32 v[84:85], v[84:85], v[128:129] op_sel_hi:[1,0] neg_lo:[0,1] neg_hi:[0,1]
	v_pk_add_f32 v[68:69], v[68:69], v[128:129] op_sel_hi:[1,0] neg_lo:[0,1] neg_hi:[0,1]
	v_pk_add_f32 v[86:87], v[86:87], v[128:129] op_sel_hi:[1,0] neg_lo:[0,1] neg_hi:[0,1]
	v_pk_add_f32 v[70:71], v[70:71], v[128:129] op_sel_hi:[1,0] neg_lo:[0,1] neg_hi:[0,1]
	v_pk_add_f32 v[88:89], v[88:89], v[128:129] op_sel_hi:[1,0] neg_lo:[0,1] neg_hi:[0,1]
	v_pk_add_f32 v[72:73], v[72:73], v[128:129] op_sel_hi:[1,0] neg_lo:[0,1] neg_hi:[0,1]
	v_pk_add_f32 v[90:91], v[90:91], v[128:129] op_sel_hi:[1,0] neg_lo:[0,1] neg_hi:[0,1]
	v_pk_add_f32 v[74:75], v[74:75], v[128:129] op_sel_hi:[1,0] neg_lo:[0,1] neg_hi:[0,1]
	v_pk_add_f32 v[92:93], v[92:93], v[128:129] op_sel_hi:[1,0] neg_lo:[0,1] neg_hi:[0,1]
	v_pk_add_f32 v[76:77], v[76:77], v[128:129] op_sel_hi:[1,0] neg_lo:[0,1] neg_hi:[0,1]
	v_pk_add_f32 v[94:95], v[94:95], v[128:129] op_sel_hi:[1,0] neg_lo:[0,1] neg_hi:[0,1]
	v_pk_add_f32 v[78:79], v[78:79], v[128:129] op_sel_hi:[1,0] neg_lo:[0,1] neg_hi:[0,1]
.LBB0_968:
	v_exp_f32_e32 v80, v80
	v_exp_f32_e32 v81, v81
	v_exp_f32_e32 v82, v82
	v_exp_f32_e32 v83, v83
	v_exp_f32_e32 v84, v84
	v_exp_f32_e32 v85, v85
	v_exp_f32_e32 v86, v86
	v_exp_f32_e32 v87, v87
	v_exp_f32_e32 v128, v64
	v_exp_f32_e32 v129, v65
	v_exp_f32_e32 v130, v66
	v_exp_f32_e32 v131, v67
	v_cvt_pk_bf16_f32 v64, v80, v81
	v_cvt_pk_bf16_f32 v65, v82, v83
	v_cvt_pk_bf16_f32 v66, v84, v85
	v_cvt_pk_bf16_f32 v67, v86, v87
	s_waitcnt lgkmcnt(0)
	v_exp_f32_e32 v138, v88
	v_exp_f32_e32 v139, v89
	v_mfma_f32_32x32x16_bf16 v[0:15], v[124:127], v[64:67], v[0:15]
	v_exp_f32_e32 v142, v90
	v_exp_f32_e32 v143, v91
	v_exp_f32_e32 v144, v92
	v_exp_f32_e32 v145, v93
	v_exp_f32_e32 v124, v94
	v_exp_f32_e32 v125, v95
	v_exp_f32_e32 v134, v68
	v_mfma_f32_32x32x16_bf16 v[16:31], v[108:111], v[64:67], v[16:31]
	v_exp_f32_e32 v135, v69
	v_exp_f32_e32 v136, v70
	v_exp_f32_e32 v137, v71
	v_cvt_pk_bf16_f32 v68, v138, v139
	v_cvt_pk_bf16_f32 v69, v142, v143
	v_cvt_pk_bf16_f32 v70, v144, v145
	v_cvt_pk_bf16_f32 v71, v124, v125
	v_exp_f32_e32 v140, v72
	v_exp_f32_e32 v141, v73
	v_mfma_f32_32x32x16_bf16 v[0:15], v[120:123], v[68:71], v[0:15]
	v_exp_f32_e32 v120, v74
	v_exp_f32_e32 v121, v75
	v_cvt_pk_bf16_f32 v72, v128, v129
	v_cvt_pk_bf16_f32 v73, v130, v131
	v_cvt_pk_bf16_f32 v74, v134, v135
	v_cvt_pk_bf16_f32 v75, v136, v137
	v_pk_add_f32 v[80:81], v[80:81], 0 op_sel_hi:[1,0]
	v_mfma_f32_32x32x16_bf16 v[16:31], v[104:107], v[68:71], v[16:31]
	v_exp_f32_e32 v122, v76
	v_exp_f32_e32 v123, v77
	v_pk_add_f32 v[80:81], v[128:129], v[80:81]
	v_cvt_pk_bf16_f32 v76, v140, v141
	v_pk_add_f32 v[80:81], v[82:83], v[80:81]
	v_cvt_pk_bf16_f32 v77, v120, v121
	v_pk_add_f32 v[80:81], v[130:131], v[80:81]
	v_mfma_f32_32x32x16_bf16 v[0:15], v[116:119], v[72:75], v[0:15]
	v_exp_f32_e32 v116, v78
	v_exp_f32_e32 v117, v79
	v_pk_add_f32 v[80:81], v[84:85], v[80:81]
	v_cvt_pk_bf16_f32 v78, v122, v123
	v_or_b32_e32 v88, s82, v216
	v_cvt_pk_bf16_f32 v79, v116, v117
	v_pk_add_f32 v[80:81], v[134:135], v[80:81]
	v_mfma_f32_32x32x16_bf16 v[16:31], v[100:103], v[72:75], v[16:31]
	v_ashrrev_i32_e32 v214, 6, v88
	s_add_i32 s2, 0, 0x10000
	v_mfma_f32_32x32x16_bf16 v[0:15], v[112:115], v[76:79], v[0:15]
	v_add_f32_e64 v112, v86, v80
	v_add_f32_e64 v113, v87, v81
	v_add_u32_e32 v115, 0x2200, v132
	v_and_b32_e32 v114, 63, v216
	v_mfma_f32_32x32x16_bf16 v[16:31], v[96:99], v[76:79], v[16:31]
	ds_read_b64 v[108:109], v115
	ds_read_b64 v[110:111], v115 offset:16
	ds_read_b64 v[104:105], v115 offset:32
	ds_read_b64 v[106:107], v115 offset:48
	ds_read_b64 v[100:101], v115 offset:64
	ds_read_b64 v[102:103], v115 offset:80
	ds_read_b64 v[96:97], v115 offset:96
	ds_read_b64 v[98:99], v115 offset:112
	ds_read_b64 v[92:93], v115 offset:0x1100
	ds_read_b64 v[94:95], v115 offset:0x1110
	ds_read_b64 v[88:89], v115 offset:0x1120
	ds_read_b64 v[90:91], v115 offset:0x1130
	ds_read_b64 v[84:85], v115 offset:0x1140
	ds_read_b64 v[86:87], v115 offset:0x1150
	ds_read_b64 v[80:81], v115 offset:0x1160
	ds_read_b64 v[82:83], v115 offset:0x1170
	s_nop 0
	s_nop 0
	s_waitcnt lgkmcnt(14)
	v_mfma_f32_32x32x16_bf16 v[48:63], v[108:111], v[64:67], v[48:63]
	v_add_f32_e64 v108, v136, v112
	v_add_f32_e64 v109, v137, v113
	v_add_f32_e64 v108, v138, v108
	v_add_f32_e64 v109, v139, v109
	v_add_f32_e64 v108, v140, v108
	v_add_f32_e64 v109, v141, v109
	v_pk_add_f32 v[108:109], v[142:143], v[108:109]
	s_waitcnt lgkmcnt(12)
	v_mfma_f32_32x32x16_bf16 v[48:63], v[104:107], v[68:71], v[48:63]
	v_add_f32_e64 v108, v120, v108
	v_add_f32_e64 v109, v121, v109
	v_add_f32_e64 v108, v144, v108
	v_add_f32_e64 v109, v145, v109
	v_mov_b32_e32 v144, v193
	v_pk_add_f32 v[108:109], v[122:123], v[108:109]
	s_nop 0
	v_pk_add_f32 v[104:105], v[124:125], v[108:109]
	s_waitcnt lgkmcnt(10)
	v_mfma_f32_32x32x16_bf16 v[48:63], v[100:103], v[72:75], v[48:63]
	v_add_f32_e64 v104, v116, v104
	v_add_f32_e64 v105, v117, v105
	v_lshlrev_b32_e32 v101, 13, v214
	v_add_f32_e32 v104, v104, v105
	v_add_f32_e32 v104, v160, v104
	v_mov_b32_e32 v105, v104
	s_nop 1
	v_permlane32_swap_b32_e32 v104, v105
	v_add_f32_e32 v100, v104, v105
	v_div_scale_f32 v102, s[0:1], v100, v100, 1.0
	v_rcp_f32_e32 v103, v102
	s_waitcnt lgkmcnt(8)
; #define LAS __attribute__((address_space(3)))
; __device__ __forceinline__ unsigned cvtpk(float lo, float hi) { f32x2 v = {lo, hi}; bf16x2_t b = __builtin_convertvector(v, bf16x2_t); return __builtin_bit_cast(unsigned, b); }
; #define otid() ((wv << 6) | olane())
; template <int DK, int DV, int VAR>
; __device__ __forceinline__ void attn_pass(LAS unsigned char* lds, const bf16_t* Qg, const bf16_t* Kg, const bf16_t* Vg, int ntiles, float cs, f32x16 (&O)[DV / 32], float& lsum, int wv) {
;     ...
;     const int tid = otid(), lane = tid & 63, wid = tid >> 6, l32 = lane & 31, hf = lane >> 5;
;     bf16x8 qf[DK / 16];
;     { const bf16_t* qrow = Qg + (size_t)(wid * 32 + l32) * DK + hf * 8;
; #pragma unroll
;       for (int kk = 0; kk < DK / 16; ++kk) qf[kk] = *(const bf16x8*)(qrow + kk * 16); }
;     const int kc0 = tid, kc1 = tid + 512;
;     const int kr0 = kc0 / KCH, kq0 = kc0 % KCH, kr1 = kc1 / KCH, kq1 = kc1 % KCH;
;     const bool k1on = (kc1 < NKC);
;     const int kp = (DV == 128 ? (wid >> 2) : ((wid >> 1) & 1)) * 16 + (lane & 15);
;     const int vch = (DV == 128 ? (wid & 3) : (wid & 1)) * 4 + (lane >> 4);
;     const bool von = (DV == 128) || (wid < 4);
;     const bf16_t* kg0 = Kg + kr0 * DK + kq0 * 8; const bf16_t* kg1 = Kg + kr1 * DK + kq1 * 8;
;     const bf16_t* vg0 = Vg + (size_t)(2 * kp) * DV + vch * 8;
;     const unsigned kl0 = kr0 * KP + kq0 * 16, kl1 = kr1 * KP + kq1 * 16, vl0 = ATT_VOFF + (vch * 8) * ATT_VP + kp * 4;
;     u32x4 ka0, ka1, va0, va1;
;     { unsigned z0 = 0u; asm volatile("" : "+v"(z0)); ka1 = (u32x4){z0, z0, z0, z0}; } va0 = ka1; va1 = ka1; ka0 = ka1;
; template <int VAR> __device__ __forceinline__ void attn_unit_a(LAS unsigned char* lds, KP p, int l, int bh, int qb, int wv) {
;     ...
;     LAS unsigned* o0 = (LAS unsigned*)(lds + 65536 + wid * 8192) + lane;
;     { const float inv = 1.f / lsum;
; #pragma unroll
;       for (int t = 0; t < 4; ++t)
; #pragma unroll
;           for (int i = 0; i < 8; ++i) o0[(t * 8 + i) * 64] = cvtpk(O[t][2 * i] * inv, O[t][2 * i + 1] * inv); }
	v_mfma_f32_32x32x16_bf16 v[48:63], v[96:99], v[76:79], v[48:63]
	v_lshlrev_b32_e32 v104, 2, v114
	v_add3_u32 v215, s2, v101, v104
	v_fma_f32 v96, -v102, v103, 1.0
	v_fmac_f32_e32 v103, v96, v103
	v_div_scale_f32 v96, vcc, 1.0, v100, 1.0
	v_mul_f32_e32 v97, v96, v103
	v_fma_f32 v98, -v102, v97, v96
	v_fmac_f32_e32 v97, v98, v103
	s_waitcnt lgkmcnt(6)
	v_mfma_f32_32x32x16_bf16 v[32:47], v[92:95], v[64:67], v[32:47]
	v_fma_f32 v64, -v102, v97, v96
	v_div_fmas_f32 v64, v64, v103, v97
	v_div_fixup_f32 v64, v64, v100, 1.0
	v_mul_f32_e64 v0, v0, v64
	v_mul_f32_e64 v1, v1, v64
	s_or_b32 s2, s27, 1
	v_cvt_pk_bf16_f32 v65, v0, v1
	v_pk_mul_f32 v[0:1], v[2:3], v[64:65] op_sel_hi:[1,0]
	s_waitcnt lgkmcnt(4)
	v_mfma_f32_32x32x16_bf16 v[32:47], v[88:91], v[68:71], v[32:47]
	v_cvt_pk_bf16_f32 v0, v0, v1
	ds_write2st64_b32 v215, v65, v0 offset1:1
	v_mul_f32_e64 v0, v4, v64
	v_mul_f32_e64 v1, v5, v64
	s_mul_i32 s0, s2, 0x900
	v_cvt_pk_bf16_f32 v2, v0, v1
	v_pk_mul_f32 v[0:1], v[6:7], v[64:65] op_sel_hi:[1,0]
	s_mul_hi_i32 s1, s2, 0x900
	v_cvt_pk_bf16_f32 v0, v0, v1
	ds_write2st64_b32 v215, v2, v0 offset0:2 offset1:3
	v_pk_mul_f32 v[0:1], v[8:9], v[64:65] op_sel_hi:[1,0]
	s_waitcnt lgkmcnt(4)
	v_mfma_f32_32x32x16_bf16 v[32:47], v[84:87], v[72:75], v[32:47]
	v_cvt_pk_bf16_f32 v2, v0, v1
	v_mul_f32_e64 v0, v10, v64
	v_mul_f32_e64 v1, v11, v64
	s_add_u32 s0, s0, s26
	v_cvt_pk_bf16_f32 v0, v0, v1
	ds_write2st64_b32 v215, v2, v0 offset0:4 offset1:5
	v_pk_mul_f32 v[0:1], v[12:13], v[64:65] op_sel_hi:[1,0]
	s_addc_u32 s1, s1, 0
	v_cvt_pk_bf16_f32 v2, v0, v1
	v_pk_mul_f32 v[0:1], v[14:15], v[64:65] op_sel_hi:[1,0]
	s_waitcnt lgkmcnt(3)
	v_mfma_f32_32x32x16_bf16 v[32:47], v[80:83], v[76:79], v[32:47]
	v_cvt_pk_bf16_f32 v0, v0, v1
	ds_write2st64_b32 v215, v2, v0 offset0:6 offset1:7
	v_mul_f32_e64 v0, v16, v64
	v_mul_f32_e64 v1, v17, v64
	s_lshl_b64 s[0:1], s[0:1], 7
	v_cvt_pk_bf16_f32 v2, v0, v1
	v_pk_mul_f32 v[0:1], v[18:19], v[64:65] op_sel_hi:[1,0]
	s_add_u32 s0, s24, s0
	v_cvt_pk_bf16_f32 v0, v0, v1
	ds_write2st64_b32 v215, v2, v0 offset0:8 offset1:9
	v_pk_mul_f32 v[0:1], v[20:21], v[64:65] op_sel_hi:[1,0]
	s_addc_u32 s1, s25, s1
	v_cvt_pk_bf16_f32 v2, v0, v1
	v_pk_mul_f32 v[0:1], v[22:23], v[64:65] op_sel_hi:[1,0]
	s_mul_hi_i32 s3, s2, 0x48000
	v_cvt_pk_bf16_f32 v0, v0, v1
	ds_write2st64_b32 v215, v2, v0 offset0:10 offset1:11
	v_pk_mul_f32 v[0:1], v[24:25], v[64:65] op_sel_hi:[1,0]
	s_mul_i32 s2, s2, 0x48000
	v_cvt_pk_bf16_f32 v2, v0, v1
	v_pk_mul_f32 v[0:1], v[26:27], v[64:65] op_sel_hi:[1,0]
	s_add_u32 s2, s22, s2
	v_cvt_pk_bf16_f32 v0, v0, v1
	ds_write2st64_b32 v215, v2, v0 offset0:12 offset1:13
	v_pk_mul_f32 v[0:1], v[28:29], v[64:65] op_sel_hi:[1,0]
	s_addc_u32 s3, s23, s3
	v_cvt_pk_bf16_f32 v2, v0, v1
	v_pk_mul_f32 v[0:1], v[30:31], v[64:65] op_sel_hi:[1,0]
	s_nop 0
	v_cvt_pk_bf16_f32 v0, v0, v1
	ds_write2st64_b32 v215, v2, v0 offset0:14 offset1:15
	v_pk_mul_f32 v[0:1], v[48:49], v[64:65] op_sel_hi:[1,0]
	s_nop 0
	v_cvt_pk_bf16_f32 v2, v0, v1
	v_pk_mul_f32 v[0:1], v[50:51], v[64:65] op_sel_hi:[1,0]
	s_nop 0
	v_cvt_pk_bf16_f32 v0, v0, v1
	ds_write2st64_b32 v215, v2, v0 offset0:16 offset1:17
	v_pk_mul_f32 v[0:1], v[52:53], v[64:65] op_sel_hi:[1,0]
	s_nop 0
	v_cvt_pk_bf16_f32 v2, v0, v1
	v_pk_mul_f32 v[0:1], v[54:55], v[64:65] op_sel_hi:[1,0]
	s_nop 0
	v_cvt_pk_bf16_f32 v0, v0, v1
	ds_write2st64_b32 v215, v2, v0 offset0:18 offset1:19
	v_pk_mul_f32 v[0:1], v[56:57], v[64:65] op_sel_hi:[1,0]
	s_nop 0
	v_cvt_pk_bf16_f32 v2, v0, v1
	v_pk_mul_f32 v[0:1], v[58:59], v[64:65] op_sel_hi:[1,0]
	s_nop 0
	v_cvt_pk_bf16_f32 v0, v0, v1
	ds_write2st64_b32 v215, v2, v0 offset0:20 offset1:21
	v_pk_mul_f32 v[0:1], v[60:61], v[64:65] op_sel_hi:[1,0]
	s_nop 0
	v_cvt_pk_bf16_f32 v2, v0, v1
	v_pk_mul_f32 v[0:1], v[62:63], v[64:65] op_sel_hi:[1,0]
	s_nop 0
	v_cvt_pk_bf16_f32 v0, v0, v1
	ds_write2st64_b32 v215, v2, v0 offset0:22 offset1:23
	v_pk_mul_f32 v[0:1], v[32:33], v[64:65] op_sel_hi:[1,0]
	s_nop 0
	v_cvt_pk_bf16_f32 v2, v0, v1
	v_pk_mul_f32 v[0:1], v[34:35], v[64:65] op_sel_hi:[1,0]
	s_nop 0
	v_cvt_pk_bf16_f32 v0, v0, v1
	ds_write2st64_b32 v215, v2, v0 offset0:24 offset1:25
	v_pk_mul_f32 v[0:1], v[36:37], v[64:65] op_sel_hi:[1,0]
	s_nop 0
	v_cvt_pk_bf16_f32 v2, v0, v1
	v_pk_mul_f32 v[0:1], v[38:39], v[64:65] op_sel_hi:[1,0]
	s_nop 0
	v_cvt_pk_bf16_f32 v0, v0, v1
	ds_write2st64_b32 v215, v2, v0 offset0:26 offset1:27
	v_pk_mul_f32 v[0:1], v[40:41], v[64:65] op_sel_hi:[1,0]
	s_nop 0
	v_cvt_pk_bf16_f32 v2, v0, v1
	v_pk_mul_f32 v[0:1], v[42:43], v[64:65] op_sel_hi:[1,0]
	s_nop 0
	v_cvt_pk_bf16_f32 v0, v0, v1
	ds_write2st64_b32 v215, v2, v0 offset0:28 offset1:29
	v_pk_mul_f32 v[0:1], v[44:45], v[64:65] op_sel_hi:[1,0]
	s_nop 0
	v_cvt_pk_bf16_f32 v2, v0, v1
	v_pk_mul_f32 v[0:1], v[46:47], v[64:65] op_sel_hi:[1,0]
	s_nop 0
	v_cvt_pk_bf16_f32 v0, v0, v1
	ds_write2st64_b32 v215, v2, v0 offset0:30 offset1:31
	v_mbcnt_lo_u32_b32 v18, -1, 0
	v_mbcnt_hi_u32_b32 v18, -1, v18
	s_nop 0
	v_or_b32_e32 v88, s67, v18
	v_ashrrev_i32_e32 v4, 6, v88
	v_and_b32_e32 v32, 31, v18
	v_lshl_or_b32 v0, v4, 5, v32
	v_ashrrev_i32_e32 v1, 31, v0
	v_bfe_u32 v19, v18, 5, 1
	v_lshlrev_b64 v[0:1], 7, v[0:1]
	v_lshl_add_u64 v[0:1], s[0:1], 0, v[0:1]
	v_lshlrev_b32_e32 v192, 4, v19
	v_lshl_add_u64 v[0:1], v[0:1], 0, v[192:193]
	global_load_dwordx4 v[140:143], v[0:1], off
	global_load_dwordx4 v[136:139], v[0:1], off offset:32
	global_load_dwordx4 v[132:135], v[0:1], off offset:64
	global_load_dwordx4 v[128:131], v[0:1], off offset:96
	v_ashrrev_i32_e32 v0, 31, v88
	v_lshrrev_b32_e32 v0, 29, v0
	v_add_u32_e32 v0, v88, v0
	v_ashrrev_i32_e32 v21, 3, v0
	v_and_b32_e32 v0, -8, v0
	v_sub_u32_e32 v20, v88, v0
	v_lshlrev_b32_e32 v76, 6, v21
	v_ashrrev_i32_e32 v77, 31, v76
	v_lshlrev_b32_e32 v78, 3, v20
	v_ashrrev_i32_e32 v79, 31, v78
	v_lshl_add_u64 v[0:1], v[76:77], 1, s[2:3]
	v_lshl_add_u64 v[12:13], v[78:79], 1, v[0:1]
	s_waitcnt lgkmcnt(0)
	s_barrier
	global_load_dwordx4 v[0:3], v[12:13], off
	v_add_u32_e32 v5, 0x200, v88
	v_ashrrev_i32_e32 v6, 31, v5
	v_lshrrev_b32_e32 v6, 29, v6
	v_add_u32_e32 v6, v5, v6
	v_ashrrev_i32_e32 v22, 3, v6
	v_and_b32_e32 v6, -8, v6
	v_sub_u32_e32 v23, v5, v6
	v_lshlrev_b32_e32 v82, 6, v22
	v_ashrrev_i32_e32 v83, 31, v82
	v_lshlrev_b32_e32 v84, 3, v23
	v_ashrrev_i32_e32 v85, 31, v84
	v_lshl_add_u64 v[6:7], v[82:83], 1, s[2:3]
	v_cmp_gt_i32_e64 s[2:3], 0, v88
	v_lshl_add_u64 v[14:15], v[84:85], 1, v[6:7]
	v_mov_b32_e32 v145, v144
	v_mov_b32_e32 v146, v144
	v_mov_b32_e32 v147, v144
	s_and_saveexec_b64 s[0:1], s[2:3]
	s_cbranch_execz .LBB0_970
	global_load_dwordx4 v[144:147], v[14:15], off

.LBB0_974:
	s_or_b64 exec, exec, s[0:1]
	v_add_co_u32_e32 v0, vcc, 0x4000, v16
	v_mad_u32_u24 v33, v32, s22, 0
	s_nop 0
	v_addc_co_u32_e32 v1, vcc, 0, v17, vcc
	v_lshlrev_b32_e32 v244, 3, v19
	v_and_b32_e32 v91, 15, v18
	global_load_dwordx4 v[152:155], v[0:1], off
	global_load_dwordx4 v[156:159], v[0:1], off offset:256
	v_add_u32_e32 v245, v33, v192
	ds_read_b128 v[0:3], v245
	ds_read_b128 v[16:19], v245 offset:0x1200
	ds_read_b128 v[34:37], v245 offset:32
	ds_read_b128 v[38:41], v245 offset:0x1220
	ds_read_b128 v[42:45], v245 offset:64
	ds_read_b128 v[46:49], v245 offset:0x1240
	ds_read_b128 v[50:53], v245 offset:96
	ds_read_b128 v[54:57], v245 offset:0x1260
	v_mul_u32_u24_e32 v246, 0x90, v32
	s_waitcnt lgkmcnt(7)
	v_mfma_f32_32x32x16_bf16 v[0:15], v[0:3], v[140:143], 0
	v_mul_u32_u24_e32 v247, 0x88, v32
	v_lshlrev_b32_e32 v32, 3, v32
	v_sub_u32_e32 v32, v33, v32
	v_add_u32_e32 v248, v32, v244
	v_add_u32_e32 v64, 0x3400, v248
	s_movk_i32 s0, 0xffe0
	s_waitcnt lgkmcnt(6)
	v_mfma_f32_32x32x16_bf16 v[16:31], v[16:19], v[140:143], 0
	s_waitcnt lgkmcnt(5)
	v_mfma_f32_32x32x16_bf16 v[0:15], v[34:37], v[136:139], v[0:15]
	s_waitcnt lgkmcnt(4)
	v_mfma_f32_32x32x16_bf16 v[16:31], v[38:41], v[136:139], v[16:31]
	s_waitcnt lgkmcnt(3)
	v_mfma_f32_32x32x16_bf16 v[0:15], v[42:45], v[132:135], v[0:15]
	s_waitcnt lgkmcnt(2)
	v_mfma_f32_32x32x16_bf16 v[16:31], v[46:49], v[132:135], v[16:31]
	s_waitcnt lgkmcnt(1)
	v_mfma_f32_32x32x16_bf16 v[0:15], v[50:53], v[128:131], v[0:15]
	s_waitcnt lgkmcnt(0)
	v_mfma_f32_32x32x16_bf16 v[16:31], v[54:57], v[128:131], v[16:31]
	ds_read_b64 v[60:61], v64
	ds_read_b64 v[62:63], v64 offset:16
	ds_read_b64 v[56:57], v64 offset:32
	ds_read_b64 v[58:59], v64 offset:48
	ds_read_b64 v[52:53], v64 offset:64
	ds_read_b64 v[54:55], v64 offset:80
	ds_read_b64 v[48:49], v64 offset:96
	ds_read_b64 v[50:51], v64 offset:112
	ds_read_b64 v[44:45], v64 offset:0x1100
	ds_read_b64 v[46:47], v64 offset:0x1110
	ds_read_b64 v[40:41], v64 offset:0x1120
	ds_read_b64 v[42:43], v64 offset:0x1130
	ds_read_b64 v[36:37], v64 offset:0x1140
	ds_read_b64 v[38:39], v64 offset:0x1150
	ds_read_b64 v[32:33], v64 offset:0x1160
	ds_read_b64 v[34:35], v64 offset:0x1170
	s_nop 10
	v_max_f32_e32 v64, v0, v16
	v_max_f32_e32 v65, v1, v17
	v_max_f32_e32 v66, v3, v19
	v_max3_f32 v66, v2, v18, v66
	v_max3_f32 v64, v64, v65, v66
	v_max_f32_e32 v65, v5, v21
	v_max_f32_e32 v66, v7, v23
	v_max3_f32 v65, v4, v20, v65
	v_max3_f32 v66, v6, v22, v66
	v_max3_f32 v64, v64, v65, v66
	v_max_f32_e32 v65, v9, v25
	v_max_f32_e32 v66, v11, v27
	v_max3_f32 v65, v8, v24, v65
	v_max3_f32 v66, v10, v26, v66
	v_max3_f32 v64, v64, v65, v66
	v_max_f32_e32 v65, v13, v29
	v_max_f32_e32 v66, v15, v31
	v_max3_f32 v65, v12, v28, v65
	v_max3_f32 v66, v14, v30, v66
	v_max3_f32 v64, v64, v65, v66
	v_mov_b32_e32 v65, v64
	s_nop 1
	v_permlane32_swap_b32_e32 v64, v65
	v_max_f32_e32 v80, v64, v65
	v_sub_f32_e32 v0, v0, v80
	v_sub_f32_e32 v1, v1, v80
	v_sub_f32_e32 v16, v16, v80
	v_sub_f32_e32 v17, v17, v80
	v_exp_f32_e32 v0, v0
	v_exp_f32_e32 v1, v1
	v_sub_f32_e32 v64, v26, v80
	v_sub_f32_e32 v65, v27, v80
	v_sub_f32_e32 v26, v2, v80
	v_sub_f32_e32 v27, v3, v80
	v_exp_f32_e32 v2, v16
	v_exp_f32_e32 v3, v17
	v_sub_f32_e32 v18, v18, v80
	v_sub_f32_e32 v19, v19, v80
	v_sub_f32_e32 v68, v30, v80
	v_sub_f32_e32 v69, v31, v80
	v_sub_f32_e32 v30, v6, v80
	v_sub_f32_e32 v31, v7, v80
	v_exp_f32_e32 v6, v26
	v_exp_f32_e32 v7, v27
	v_sub_f32_e32 v66, v28, v80
	v_sub_f32_e32 v67, v29, v80
	v_sub_f32_e32 v28, v4, v80
	v_sub_f32_e32 v29, v5, v80
	v_sub_f32_e32 v70, v8, v80
	v_sub_f32_e32 v71, v9, v80
	v_exp_f32_e32 v8, v18
	v_exp_f32_e32 v9, v19
	v_sub_f32_e32 v20, v20, v80
	v_sub_f32_e32 v21, v21, v80
	v_sub_f32_e32 v72, v10, v80
	v_sub_f32_e32 v73, v11, v80
	v_pk_add_f32 v[4:5], v[0:1], 0 op_sel_hi:[1,0]
	v_exp_f32_e32 v10, v28
	v_exp_f32_e32 v11, v29
	v_sub_f32_e32 v74, v12, v80
	v_sub_f32_e32 v75, v13, v80
	v_pk_add_f32 v[4:5], v[2:3], v[4:5]
	v_exp_f32_e32 v12, v20
	v_exp_f32_e32 v13, v21
	v_sub_f32_e32 v22, v22, v80
	v_sub_f32_e32 v23, v23, v80
	v_sub_f32_e32 v81, v14, v80
	v_sub_f32_e32 v86, v15, v80
	v_pk_add_f32 v[4:5], v[6:7], v[4:5]
	v_exp_f32_e32 v14, v30
	v_exp_f32_e32 v15, v31
	v_pk_add_f32 v[4:5], v[8:9], v[4:5]
	v_exp_f32_e32 v20, v22
	v_exp_f32_e32 v21, v23
	v_sub_f32_e32 v24, v24, v80
	v_sub_f32_e32 v25, v25, v80
	v_pk_add_f32 v[4:5], v[10:11], v[4:5]
	v_exp_f32_e32 v22, v70
	v_exp_f32_e32 v23, v71
	v_pk_add_f32 v[4:5], v[12:13], v[4:5]
	v_exp_f32_e32 v24, v24
	v_exp_f32_e32 v25, v25
	v_pk_add_f32 v[4:5], v[14:15], v[4:5]
	v_exp_f32_e32 v26, v72
	v_exp_f32_e32 v27, v73
	v_pk_add_f32 v[4:5], v[20:21], v[4:5]
	v_exp_f32_e32 v28, v64
	v_exp_f32_e32 v29, v65
	v_pk_add_f32 v[4:5], v[22:23], v[4:5]
	v_exp_f32_e32 v30, v74
	v_exp_f32_e32 v31, v75
	v_pk_add_f32 v[4:5], v[24:25], v[4:5]
	v_exp_f32_e32 v70, v66
	v_exp_f32_e32 v71, v67
	v_pk_add_f32 v[4:5], v[26:27], v[4:5]
	v_exp_f32_e32 v64, v81
	v_exp_f32_e32 v65, v86
	v_pk_add_f32 v[4:5], v[28:29], v[4:5]
	v_exp_f32_e32 v92, v68
	v_exp_f32_e32 v93, v69
	v_pk_add_f32 v[4:5], v[30:31], v[4:5]
	v_cvt_pk_bf16_f32 v16, v0, v1
	v_pk_add_f32 v[4:5], v[70:71], v[4:5]
	v_cvt_pk_bf16_f32 v17, v6, v7
	v_pk_add_f32 v[4:5], v[64:65], v[4:5]
	v_cvt_pk_bf16_f32 v18, v10, v11
	v_pk_add_f32 v[4:5], v[92:93], v[4:5]
	v_cvt_pk_bf16_f32 v19, v14, v15
	v_pk_add_f32 v[86:87], v[4:5], v[4:5] op_sel_hi:[0,1]
	v_cvt_pk_bf16_f32 v75, v64, v65
	v_cvt_pk_bf16_f32 v64, v2, v3
	v_cvt_pk_bf16_f32 v65, v8, v9
	v_cvt_pk_bf16_f32 v66, v12, v13
	s_waitcnt lgkmcnt(14)
	v_mfma_f32_32x32x16_bf16 v[0:15], v[60:63], v[16:19], 0
	v_cvt_pk_bf16_f32 v72, v22, v23
	v_cvt_pk_bf16_f32 v73, v26, v27
	v_cvt_pk_bf16_f32 v74, v30, v31
	v_cvt_pk_bf16_f32 v67, v20, v21
	v_cvt_pk_bf16_f32 v68, v24, v25
	v_cvt_pk_bf16_f32 v69, v28, v29
	v_cvt_pk_bf16_f32 v70, v70, v71
	s_waitcnt lgkmcnt(12)
	v_mfma_f32_32x32x16_bf16 v[0:15], v[56:59], v[72:75], v[0:15]
	v_cvt_pk_bf16_f32 v71, v92, v93
	v_mov_b32_e32 v81, v87
	v_add_f32_e64 v210, v80, 0
	v_add_f32_e64 v211, v81, 0
	v_add_f32_e64 v80, -v210, neg(0)
	v_add_f32_e64 v81, -v211, neg(0)
	v_mov_b32_e32 v81, v80
	s_waitcnt lgkmcnt(10)
	v_mfma_f32_32x32x16_bf16 v[0:15], v[52:55], v[64:67], v[0:15]
	v_mov_b32_e32 v86, v80
	v_mov_b32_e32 v87, v80
	s_waitcnt lgkmcnt(8)
	v_mfma_f32_32x32x16_bf16 v[0:15], v[48:51], v[68:71], v[0:15]
	s_waitcnt lgkmcnt(6)
	v_mfma_f32_32x32x16_bf16 v[48:63], v[44:47], v[16:19], 0
	s_waitcnt lgkmcnt(4)
	v_mfma_f32_32x32x16_bf16 v[48:63], v[40:43], v[72:75], v[48:63]
	s_waitcnt lgkmcnt(2)
	v_mfma_f32_32x32x16_bf16 v[48:63], v[36:39], v[64:67], v[48:63]
	v_add_u32_e32 v36, 0x5600, v248
	s_waitcnt lgkmcnt(0)
	v_mfma_f32_32x32x16_bf16 v[48:63], v[32:35], v[68:71], v[48:63]
	ds_read_b64 v[32:33], v36
	ds_read_b64 v[34:35], v36 offset:16
	ds_read_b64 v[104:105], v36 offset:32
	ds_read_b64 v[106:107], v36 offset:48
	ds_read_b64 v[28:29], v36 offset:64
	ds_read_b64 v[30:31], v36 offset:80
	ds_read_b64 v[24:25], v36 offset:96
	ds_read_b64 v[26:27], v36 offset:112
	ds_read_b64 v[20:21], v36 offset:0x1100
	ds_read_b64 v[22:23], v36 offset:0x1110
	ds_read_b64 v[100:101], v36 offset:0x1120
	ds_read_b64 v[102:103], v36 offset:0x1130
	ds_read_b64 v[96:97], v36 offset:0x1140
	ds_read_b64 v[98:99], v36 offset:0x1150
	ds_read_b64 v[92:93], v36 offset:0x1160
	ds_read_b64 v[94:95], v36 offset:0x1170
	s_nop 0
	s_nop 0
	s_waitcnt lgkmcnt(14)
	v_mfma_f32_32x32x16_bf16 v[32:47], v[32:35], v[16:19], 0
	s_waitcnt lgkmcnt(12)
	v_mfma_f32_32x32x16_bf16 v[32:47], v[104:107], v[72:75], v[32:47]
	s_waitcnt lgkmcnt(10)
	v_mfma_f32_32x32x16_bf16 v[32:47], v[28:31], v[64:67], v[32:47]
	s_waitcnt lgkmcnt(8)
	v_mfma_f32_32x32x16_bf16 v[32:47], v[24:27], v[68:71], v[32:47]
	s_waitcnt lgkmcnt(6)
	v_mfma_f32_32x32x16_bf16 v[16:31], v[20:23], v[16:19], 0
	s_waitcnt lgkmcnt(4)
	v_mfma_f32_32x32x16_bf16 v[16:31], v[100:103], v[72:75], v[16:31]
	s_waitcnt lgkmcnt(2)
	v_mfma_f32_32x32x16_bf16 v[16:31], v[96:99], v[64:67], v[16:31]
	v_lshlrev_b32_e32 v64, 1, v90
	v_lshlrev_b32_e32 v65, 1, v91
	v_and_or_b32 v64, v64, s0, v65
	v_ashrrev_i32_e32 v65, 31, v64
	v_lshlrev_b64 v[64:65], 8, v[64:65]
	v_lshlrev_b32_e32 v66, 4, v89
	s_add_u32 s0, s21, 0x964c000
	s_waitcnt lgkmcnt(0)
	v_mfma_f32_32x32x16_bf16 v[16:31], v[92:95], v[68:71], v[16:31]
	v_lshl_add_u64 v[64:65], s[8:9], 0, v[64:65]
	v_and_or_b32 v66, v88, s69, v66
	v_mov_b32_e32 v67, v193
	s_addc_u32 s1, s20, 0
	v_lshl_add_u64 v[204:205], v[64:65], 0, v[66:67]
	v_lshl_add_u64 v[64:65], v[82:83], 1, s[0:1]
	v_lshl_add_u64 v[206:207], v[84:85], 1, v[64:65]
	v_lshl_add_u64 v[64:65], v[76:77], 1, s[0:1]
	v_lshl_add_u64 v[208:209], v[78:79], 1, v[64:65]
	s_mov_b32 s8, 0x8000
	v_mov_b32_e32 v82, v80
	v_mov_b32_e32 v83, v80
	v_mov_b32_e32 v84, v80
	v_mov_b32_e32 v85, v80
	v_mov_b32_e32 v88, v80
	v_mov_b32_e32 v89, v80
	v_mov_b32_e32 v90, v80
	v_mov_b32_e32 v91, v80
	v_mov_b32_e32 v92, v80
	v_mov_b32_e32 v93, v80
	v_mov_b32_e32 v94, v80
	v_mov_b32_e32 v95, v80

.LBB0_979:
	s_or_b64 exec, exec, s[0:1]
	v_lshl_add_u64 v[64:65], s[4:5], 0, v[204:205]
	v_add_co_u32_e32 v64, vcc, 0xa808000, v64
	v_add3_u32 v96, s9, v246, v192
	s_nop 0
	v_addc_co_u32_e32 v65, vcc, 0, v65, vcc
	global_load_dwordx4 v[152:155], v[64:65], off
	global_load_dwordx4 v[156:159], v[64:65], off offset:256
	ds_read_b128 v[64:67], v96
	ds_read_b128 v[68:71], v96 offset:0x1200
	ds_read_b128 v[72:75], v96 offset:32
	ds_read_b128 v[76:79], v96 offset:0x1220
	ds_read_b128 v[160:163], v96 offset:64
	ds_read_b128 v[164:167], v96 offset:0x1240
	ds_read_b128 v[168:171], v96 offset:96
	ds_read_b128 v[172:175], v96 offset:0x1260
	v_mov_b32_e32 v254, 0xc00
	s_waitcnt lgkmcnt(7)
	v_mfma_f32_32x32x16_bf16 v[112:127], v[64:67], v[140:143], v[80:95]
	v_add_u32_e32 v64, s9, v247
	v_add3_u32 v249, v64, v244, s87
	s_waitcnt lgkmcnt(6)
	v_mfma_f32_32x32x16_bf16 v[96:111], v[68:71], v[140:143], v[80:95]
	s_waitcnt lgkmcnt(5)
	v_mfma_f32_32x32x16_bf16 v[112:127], v[72:75], v[136:139], v[112:127]
	s_waitcnt lgkmcnt(4)
	v_mfma_f32_32x32x16_bf16 v[96:111], v[76:79], v[136:139], v[96:111]
	s_waitcnt lgkmcnt(3)
	v_mfma_f32_32x32x16_bf16 v[112:127], v[160:163], v[132:135], v[112:127]
	s_waitcnt lgkmcnt(2)
	v_mfma_f32_32x32x16_bf16 v[96:111], v[164:167], v[132:135], v[96:111]
	s_waitcnt lgkmcnt(1)
	v_mfma_f32_32x32x16_bf16 v[112:127], v[168:171], v[128:131], v[112:127]
	s_waitcnt lgkmcnt(0)
	v_mfma_f32_32x32x16_bf16 v[96:111], v[172:175], v[128:131], v[96:111]
	s_nop 10
	ds_read_b64 v[188:189], v249
	ds_read_b64 v[190:191], v249 offset:16
	ds_read_b64 v[184:185], v249 offset:32
	ds_read_b64 v[186:187], v249 offset:48
	ds_read_b64 v[180:181], v249 offset:64
	ds_read_b64 v[182:183], v249 offset:80
	ds_read_b64 v[176:177], v249 offset:96
	ds_read_b64 v[178:179], v249 offset:112
	ds_read_b64 v[172:173], v249 offset:0x1100
	ds_read_b64 v[174:175], v249 offset:0x1110
	ds_read_b64 v[168:169], v249 offset:0x1120
	ds_read_b64 v[170:171], v249 offset:0x1130
	ds_read_b64 v[164:165], v249 offset:0x1140
	ds_read_b64 v[166:167], v249 offset:0x1150
	ds_read_b64 v[160:161], v249 offset:0x1160
	ds_read_b64 v[162:163], v249 offset:0x1170
	v_max_f32_e32 v64, v112, v96
	v_max_f32_e32 v65, v113, v97
	v_max_f32_e32 v66, v115, v99
	v_max3_f32 v66, v114, v98, v66
	v_max3_f32 v64, v64, v65, v66
	v_max_f32_e32 v65, v117, v101
	v_max_f32_e32 v66, v119, v103
	v_max3_f32 v65, v116, v100, v65
	v_max3_f32 v66, v118, v102, v66
	v_max3_f32 v64, v64, v65, v66
	v_max_f32_e32 v65, v121, v105
	v_max_f32_e32 v66, v123, v107
	v_max3_f32 v65, v120, v104, v65
	v_max3_f32 v66, v122, v106, v66
	v_max3_f32 v64, v64, v65, v66
	v_max_f32_e32 v65, v125, v109
	v_max_f32_e32 v67, v127, v127
	v_max_f32_e32 v66, v67, v111
	v_max3_f32 v65, v124, v108, v65
	v_max3_f32 v66, v126, v110, v66
	v_max3_f32 v64, v64, v65, v66
	v_mov_b32_e32 v65, v64
	s_nop 1
	v_permlane32_swap_b32_e32 v64, v65
	v_max_f32_e32 v64, v64, v65
	v_cmp_lt_f32_e32 vcc, s80, v64
	s_cbranch_vccz .LBB0_981
	v_max_f32_e32 v80, 0, v64
	v_exp_f32_e64 v64, -v80
	s_nop 0
	v_mov_b32_e32 v81, v64
	v_pk_mul_f32 v[14:15], v[14:15], v[64:65] op_sel_hi:[1,0]
	v_pk_mul_f32 v[12:13], v[12:13], v[64:65] op_sel_hi:[1,0]
	v_pk_mul_f32 v[10:11], v[10:11], v[64:65] op_sel_hi:[1,0]
	v_pk_mul_f32 v[8:9], v[8:9], v[64:65] op_sel_hi:[1,0]
	v_pk_mul_f32 v[6:7], v[6:7], v[64:65] op_sel_hi:[1,0]
	v_pk_mul_f32 v[4:5], v[4:5], v[64:65] op_sel_hi:[1,0]
	v_pk_mul_f32 v[2:3], v[2:3], v[64:65] op_sel_hi:[1,0]
	v_pk_mul_f32 v[0:1], v[0:1], v[64:65] op_sel_hi:[1,0]
	v_pk_mul_f32 v[62:63], v[62:63], v[64:65] op_sel_hi:[1,0]
	v_pk_mul_f32 v[60:61], v[60:61], v[64:65] op_sel_hi:[1,0]
	v_pk_mul_f32 v[58:59], v[58:59], v[64:65] op_sel_hi:[1,0]
	v_pk_mul_f32 v[56:57], v[56:57], v[64:65] op_sel_hi:[1,0]
	v_pk_mul_f32 v[54:55], v[54:55], v[64:65] op_sel_hi:[1,0]
	v_pk_mul_f32 v[52:53], v[52:53], v[64:65] op_sel_hi:[1,0]
	v_pk_mul_f32 v[50:51], v[50:51], v[64:65] op_sel_hi:[1,0]
	v_pk_mul_f32 v[48:49], v[48:49], v[64:65] op_sel_hi:[1,0]
	v_pk_mul_f32 v[46:47], v[46:47], v[64:65] op_sel_hi:[1,0]
	v_pk_mul_f32 v[44:45], v[44:45], v[64:65] op_sel_hi:[1,0]
	v_pk_mul_f32 v[42:43], v[42:43], v[64:65] op_sel_hi:[1,0]
	v_pk_mul_f32 v[40:41], v[40:41], v[64:65] op_sel_hi:[1,0]
	v_pk_mul_f32 v[38:39], v[38:39], v[64:65] op_sel_hi:[1,0]
	v_pk_mul_f32 v[36:37], v[36:37], v[64:65] op_sel_hi:[1,0]
	v_pk_mul_f32 v[34:35], v[34:35], v[64:65] op_sel_hi:[1,0]
	v_pk_mul_f32 v[32:33], v[32:33], v[64:65] op_sel_hi:[1,0]
	v_pk_mul_f32 v[30:31], v[30:31], v[64:65] op_sel_hi:[1,0]
	v_pk_mul_f32 v[28:29], v[28:29], v[64:65] op_sel_hi:[1,0]
	v_pk_mul_f32 v[26:27], v[26:27], v[64:65] op_sel_hi:[1,0]
	v_pk_mul_f32 v[24:25], v[24:25], v[64:65] op_sel_hi:[1,0]
	v_pk_mul_f32 v[22:23], v[22:23], v[64:65] op_sel_hi:[1,0]
	v_pk_mul_f32 v[20:21], v[20:21], v[64:65] op_sel_hi:[1,0]
	v_pk_mul_f32 v[18:19], v[18:19], v[64:65] op_sel_hi:[1,0]
	v_pk_mul_f32 v[16:17], v[16:17], v[64:65] op_sel_hi:[1,0]
	v_pk_add_f32 v[212:213], v[210:211], v[80:81]
	v_pk_mul_f32 v[64:65], v[210:211], v[80:81]
	v_pk_add_f32 v[112:113], v[112:113], v[80:81] op_sel_hi:[1,0] neg_lo:[0,1] neg_hi:[0,1]
	v_mov_b32_e32 v213, v65
	v_pk_add_f32 v[64:65], v[212:213], 0 neg_lo:[1,1] neg_hi:[1,1]
	v_pk_add_f32 v[96:97], v[96:97], v[80:81] op_sel_hi:[1,0] neg_lo:[0,1] neg_hi:[0,1]
	v_pk_add_f32 v[114:115], v[114:115], v[80:81] op_sel_hi:[1,0] neg_lo:[0,1] neg_hi:[0,1]
	v_pk_add_f32 v[98:99], v[98:99], v[80:81] op_sel_hi:[1,0] neg_lo:[0,1] neg_hi:[0,1]
	v_pk_add_f32 v[116:117], v[116:117], v[80:81] op_sel_hi:[1,0] neg_lo:[0,1] neg_hi:[0,1]
	v_pk_add_f32 v[100:101], v[100:101], v[80:81] op_sel_hi:[1,0] neg_lo:[0,1] neg_hi:[0,1]
	v_pk_add_f32 v[118:119], v[118:119], v[80:81] op_sel_hi:[1,0] neg_lo:[0,1] neg_hi:[0,1]
	v_pk_add_f32 v[102:103], v[102:103], v[80:81] op_sel_hi:[1,0] neg_lo:[0,1] neg_hi:[0,1]
	v_pk_add_f32 v[120:121], v[120:121], v[80:81] op_sel_hi:[1,0] neg_lo:[0,1] neg_hi:[0,1]
	v_pk_add_f32 v[104:105], v[104:105], v[80:81] op_sel_hi:[1,0] neg_lo:[0,1] neg_hi:[0,1]
	v_pk_add_f32 v[122:123], v[122:123], v[80:81] op_sel_hi:[1,0] neg_lo:[0,1] neg_hi:[0,1]
	v_pk_add_f32 v[106:107], v[106:107], v[80:81] op_sel_hi:[1,0] neg_lo:[0,1] neg_hi:[0,1]
	v_pk_add_f32 v[124:125], v[124:125], v[80:81] op_sel_hi:[1,0] neg_lo:[0,1] neg_hi:[0,1]
	v_pk_add_f32 v[108:109], v[108:109], v[80:81] op_sel_hi:[1,0] neg_lo:[0,1] neg_hi:[0,1]
	v_mov_b32_e32 v65, v64
	v_mov_b32_e32 v66, v64
	v_mov_b32_e32 v67, v64
	v_mov_b32_e32 v68, v64
	v_mov_b32_e32 v69, v64
	v_mov_b32_e32 v70, v64
	v_mov_b32_e32 v71, v64
	v_mov_b32_e32 v72, v64
	v_mov_b32_e32 v73, v64
	v_mov_b32_e32 v74, v64
	v_mov_b32_e32 v75, v64
	v_mov_b32_e32 v76, v64
	v_mov_b32_e32 v77, v64
	v_mov_b32_e32 v78, v64
	v_mov_b32_e32 v79, v64
	v_pk_add_f32 v[126:127], v[126:127], v[80:81] op_sel_hi:[1,0] neg_lo:[0,1] neg_hi:[0,1]
	v_pk_add_f32 v[110:111], v[110:111], v[80:81] op_sel_hi:[1,0] neg_lo:[0,1] neg_hi:[0,1]
	v_mov_b32_e32 v80, v64
	v_mov_b32_e32 v81, v64
	v_mov_b32_e32 v82, v64
	v_mov_b32_e32 v83, v64
	v_mov_b32_e32 v84, v64
	v_mov_b32_e32 v85, v64
	v_mov_b32_e32 v86, v64
	v_mov_b32_e32 v87, v64
	v_mov_b32_e32 v88, v64
	v_mov_b32_e32 v89, v64
	v_mov_b32_e32 v90, v64
	v_mov_b32_e32 v91, v64
	v_mov_b32_e32 v92, v64
	v_mov_b32_e32 v93, v64
	v_mov_b32_e32 v94, v64
	v_mov_b32_e32 v95, v64
	v_mov_b32_e32 v210, v212
	s_branch .LBB0_982

.LBB0_982:
	v_exp_f32_e32 v232, v112
	v_exp_f32_e32 v233, v113
	v_exp_f32_e32 v96, v96
	v_exp_f32_e32 v97, v97
	v_exp_f32_e32 v114, v114
	v_exp_f32_e32 v115, v115
	v_exp_f32_e32 v98, v98
	v_exp_f32_e32 v99, v99
	v_pk_add_f32 v[112:113], v[232:233], 0 op_sel_hi:[1,0]
	v_exp_f32_e32 v116, v116
	v_exp_f32_e32 v117, v117
	v_pk_add_f32 v[112:113], v[96:97], v[112:113]
	v_exp_f32_e32 v100, v100
	v_exp_f32_e32 v101, v101
	v_pk_add_f32 v[112:113], v[114:115], v[112:113]
	v_exp_f32_e32 v118, v118
	v_exp_f32_e32 v119, v119
	v_pk_add_f32 v[112:113], v[98:99], v[112:113]
	v_exp_f32_e32 v102, v102
	v_exp_f32_e32 v103, v103
	v_pk_add_f32 v[112:113], v[116:117], v[112:113]
	v_exp_f32_e32 v120, v120
	v_exp_f32_e32 v121, v121
	v_pk_add_f32 v[112:113], v[100:101], v[112:113]
	v_exp_f32_e32 v250, v104
	v_exp_f32_e32 v251, v105
	v_pk_add_f32 v[112:113], v[118:119], v[112:113]
	v_exp_f32_e32 v122, v122
	v_exp_f32_e32 v123, v123
	v_pk_add_f32 v[112:113], v[102:103], v[112:113]
	v_exp_f32_e32 v252, v106
	v_exp_f32_e32 v253, v107
	v_pk_add_f32 v[104:105], v[120:121], v[112:113]
	v_exp_f32_e32 v106, v124
	v_exp_f32_e32 v107, v125
	v_exp_f32_e32 v124, v108
	v_exp_f32_e32 v125, v109
	v_exp_f32_e32 v234, v110
	v_exp_f32_e32 v235, v111
	v_cvt_pk_bf16_f32 v108, v232, v233
	v_cvt_pk_bf16_f32 v109, v114, v115
	v_cvt_pk_bf16_f32 v110, v116, v117
	v_cvt_pk_bf16_f32 v111, v118, v119
	v_pk_add_f32 v[104:105], v[250:251], v[104:105]
	s_waitcnt lgkmcnt(0)
	v_exp_f32_e32 v126, v126
	v_mfma_f32_32x32x16_bf16 v[0:15], v[188:191], v[108:111], v[0:15]
	v_add_f32_e64 v104, v122, v104
	v_add_f32_e64 v105, v123, v105
	v_exp_f32_e32 v127, v127
	v_pk_add_f32 v[104:105], v[252:253], v[104:105]
	v_cvt_pk_bf16_f32 v96, v96, v97
	v_pk_add_f32 v[104:105], v[106:107], v[104:105]
	v_cvt_pk_bf16_f32 v106, v106, v107
	v_pk_add_f32 v[104:105], v[124:125], v[104:105]
	v_mfma_f32_32x32x16_bf16 v[48:63], v[172:175], v[108:111], v[48:63]
	v_add_f32_e64 v104, v126, v104
	v_add_f32_e64 v105, v127, v105
	v_cvt_pk_bf16_f32 v107, v126, v127
	v_add_f32_e64 v104, v234, v104
	v_add_f32_e64 v105, v235, v105
	v_cvt_pk_bf16_f32 v97, v98, v99
	v_pk_add_f32 v[112:113], v[104:105], v[104:105] op_sel:[0,1] op_sel_hi:[1,0]
	v_cvt_pk_bf16_f32 v104, v120, v121
	v_cvt_pk_bf16_f32 v105, v122, v123
	v_cvt_pk_bf16_f32 v98, v100, v101
	v_cvt_pk_bf16_f32 v99, v102, v103
	v_mfma_f32_32x32x16_bf16 v[0:15], v[184:187], v[104:107], v[0:15]
	v_cvt_pk_bf16_f32 v100, v250, v251
	v_cvt_pk_bf16_f32 v101, v252, v253
	v_cvt_pk_bf16_f32 v102, v124, v125
	v_cvt_pk_bf16_f32 v103, v234, v235
	v_add_u32_e32 v126, 0x2200, v249
	s_add_i32 s8, s8, 0x8000
	v_lshl_add_u64 v[204:205], v[204:205], 0, s[70:71]
	v_mfma_f32_32x32x16_bf16 v[48:63], v[168:171], v[104:107], v[48:63]
	v_lshl_add_u64 v[206:207], v[206:207], 0, s[94:95]
	v_lshl_add_u64 v[208:209], v[208:209], 0, s[94:95]
	s_cmp_lg_u32 s8, 0x118000
	v_mfma_f32_32x32x16_bf16 v[0:15], v[180:183], v[96:99], v[0:15]
	v_mfma_f32_32x32x16_bf16 v[48:63], v[164:167], v[96:99], v[48:63]
	v_mfma_f32_32x32x16_bf16 v[0:15], v[176:179], v[100:103], v[0:15]
	v_mfma_f32_32x32x16_bf16 v[48:63], v[160:163], v[100:103], v[48:63]
	ds_read_b64 v[176:177], v126
	ds_read_b64 v[178:179], v126 offset:16
	ds_read_b64 v[172:173], v126 offset:32
	ds_read_b64 v[174:175], v126 offset:48
	ds_read_b64 v[168:169], v126 offset:64
	ds_read_b64 v[170:171], v126 offset:80
	ds_read_b64 v[164:165], v126 offset:96
	ds_read_b64 v[166:167], v126 offset:112
	ds_read_b64 v[160:161], v126 offset:0x1100
	ds_read_b64 v[162:163], v126 offset:0x1110
	ds_read_b64 v[122:123], v126 offset:0x1120
	ds_read_b64 v[124:125], v126 offset:0x1130
	ds_read_b64 v[118:119], v126 offset:0x1140
	ds_read_b64 v[120:121], v126 offset:0x1150
	ds_read_b64 v[114:115], v126 offset:0x1160
	ds_read_b64 v[116:117], v126 offset:0x1170
	s_nop 0
	s_nop 0
	s_waitcnt lgkmcnt(14)
	v_mfma_f32_32x32x16_bf16 v[32:47], v[176:179], v[108:111], v[32:47]
	s_waitcnt lgkmcnt(6)
	v_mfma_f32_32x32x16_bf16 v[16:31], v[160:163], v[108:111], v[16:31]
	v_add_f32_e64 v160, v213, v112
	v_add_f32_e64 v161, v212, v113
	v_mfma_f32_32x32x16_bf16 v[32:47], v[172:175], v[104:107], v[32:47]
	s_waitcnt lgkmcnt(4)
	v_mfma_f32_32x32x16_bf16 v[16:31], v[122:125], v[104:107], v[16:31]
	v_mfma_f32_32x32x16_bf16 v[32:47], v[168:171], v[96:99], v[32:47]
	s_waitcnt lgkmcnt(2)
	v_mfma_f32_32x32x16_bf16 v[16:31], v[118:121], v[96:99], v[16:31]
	v_mfma_f32_32x32x16_bf16 v[32:47], v[164:167], v[100:103], v[32:47]
	s_waitcnt lgkmcnt(0)
	v_mfma_f32_32x32x16_bf16 v[16:31], v[114:117], v[100:103], v[16:31]
	s_cbranch_scc0 .LBB0_984
	v_mov_b32_e32 v211, v160
	s_branch .LBB0_975
.LBB0_984:
	v_mov_b64_e32 v[64:65], v[80:81]
	v_mov_b64_e32 v[66:67], v[82:83]
	v_mov_b64_e32 v[68:69], v[84:85]
	v_mov_b64_e32 v[70:71], v[86:87]
	v_mov_b64_e32 v[72:73], v[88:89]
	v_mov_b64_e32 v[74:75], v[90:91]
	v_mov_b64_e32 v[76:77], v[92:93]
	v_mov_b64_e32 v[78:79], v[94:95]
	s_waitcnt vmcnt(2)
	ds_write_b128 v240, v[148:151] offset:32768
	s_and_saveexec_b64 s[0:1], s[2:3]
	ds_write_b128 v219, v[144:147] offset:32768
	s_or_b64 exec, exec, s[0:1]
	s_waitcnt vmcnt(0)
	v_perm_b32 v80, v156, v152, s85
	v_perm_b32 v81, v156, v152, s86
	v_add_u32_e32 v82, 0xb400, v241
	ds_write2_b32 v82, v80, v81 offset1:34
	v_perm_b32 v80, v157, v153, s85
	v_perm_b32 v81, v157, v153, s86
	ds_write2_b32 v82, v80, v81 offset0:68 offset1:102
	v_perm_b32 v80, v158, v154, s85
	v_perm_b32 v81, v158, v154, s86
	ds_write2_b32 v82, v80, v81 offset0:136 offset1:170
	v_perm_b32 v80, v159, v155, s85
	v_perm_b32 v81, v159, v155, s86
	ds_write2_b32 v82, v80, v81 offset0:204 offset1:238
	v_add_u32_e32 v80, 0x8000, v245
	s_waitcnt lgkmcnt(0)
	s_barrier
	ds_read_b128 v[96:99], v80
	ds_read_b128 v[100:103], v80 offset:0x1200
	ds_read_b128 v[104:107], v80 offset:32
	ds_read_b128 v[108:111], v80 offset:0x1220
	ds_read_b128 v[112:115], v80 offset:64
	ds_read_b128 v[116:119], v80 offset:0x1240
	ds_read_b128 v[144:147], v80 offset:96
	ds_read_b128 v[120:123], v80 offset:0x1260
	s_nop 0
	s_waitcnt lgkmcnt(7)
	v_mfma_f32_32x32x16_bf16 v[80:95], v[96:99], v[140:143], v[64:79]
	s_waitcnt lgkmcnt(6)
	v_mfma_f32_32x32x16_bf16 v[64:79], v[100:103], v[140:143], v[64:79]
	s_waitcnt lgkmcnt(5)
	v_mfma_f32_32x32x16_bf16 v[80:95], v[104:107], v[136:139], v[80:95]
	s_waitcnt lgkmcnt(4)
	v_mfma_f32_32x32x16_bf16 v[64:79], v[108:111], v[136:139], v[64:79]
	s_waitcnt lgkmcnt(3)
	v_mfma_f32_32x32x16_bf16 v[80:95], v[112:115], v[132:135], v[80:95]
	s_waitcnt lgkmcnt(2)
	v_mfma_f32_32x32x16_bf16 v[64:79], v[116:119], v[132:135], v[64:79]
	v_add_u32_e32 v132, 0xb400, v248
	s_waitcnt lgkmcnt(0)
	v_mfma_f32_32x32x16_bf16 v[64:79], v[120:123], v[128:131], v[64:79]
	ds_read_b64 v[124:125], v132
	ds_read_b64 v[126:127], v132 offset:16
	ds_read_b64 v[120:121], v132 offset:32
	ds_read_b64 v[122:123], v132 offset:48
	ds_read_b64 v[116:117], v132 offset:64
	ds_read_b64 v[118:119], v132 offset:80
	ds_read_b64 v[112:113], v132 offset:96
	ds_read_b64 v[114:115], v132 offset:112
	ds_read_b64 v[108:109], v132 offset:0x1100
	ds_read_b64 v[110:111], v132 offset:0x1110
	ds_read_b64 v[104:105], v132 offset:0x1120
	ds_read_b64 v[106:107], v132 offset:0x1130
	ds_read_b64 v[100:101], v132 offset:0x1140
	ds_read_b64 v[102:103], v132 offset:0x1150
	ds_read_b64 v[96:97], v132 offset:0x1160
	ds_read_b64 v[98:99], v132 offset:0x1170
	v_mfma_f32_32x32x16_bf16 v[80:95], v[144:147], v[128:131], v[80:95]
	s_nop 10
	v_max_f32_e32 v133, v64, v64
	v_max_f32_e32 v129, v81, v65
	v_max_f32_e32 v130, v83, v67
	v_max_f32_e32 v128, v80, v133
	v_max3_f32 v130, v82, v66, v130
	v_max3_f32 v128, v128, v129, v130
	v_max_f32_e32 v129, v85, v69
	v_max_f32_e32 v130, v87, v71
	v_max3_f32 v129, v84, v68, v129
	v_max3_f32 v130, v86, v70, v130
	v_max3_f32 v128, v128, v129, v130
	v_max_f32_e32 v129, v89, v73
	v_max_f32_e32 v130, v91, v75
	v_max3_f32 v129, v88, v72, v129
	v_max3_f32 v130, v90, v74, v130
	v_max3_f32 v128, v128, v129, v130
	v_max_f32_e32 v129, v93, v77
	v_max_f32_e32 v131, v95, v95
	v_max_f32_e32 v130, v131, v79
	v_max3_f32 v129, v92, v76, v129
	v_max3_f32 v130, v94, v78, v130
	v_max3_f32 v128, v128, v129, v130
	v_mov_b32_e32 v129, v128
	s_nop 1
	v_permlane32_swap_b32_e32 v128, v129
	v_max_f32_e32 v128, v128, v129
	v_cmp_lt_f32_e32 vcc, s80, v128
	s_cbranch_vccz .LBB0_822
	v_max_f32_e32 v128, 0, v128
	v_exp_f32_e64 v130, -v128
	v_pk_add_f32 v[80:81], v[80:81], v[128:129] op_sel_hi:[1,0] neg_lo:[0,1] neg_hi:[0,1]
	v_pk_add_f32 v[64:65], v[64:65], v[128:129] op_sel_hi:[1,0] neg_lo:[0,1] neg_hi:[0,1]
	v_pk_add_f32 v[82:83], v[82:83], v[128:129] op_sel_hi:[1,0] neg_lo:[0,1] neg_hi:[0,1]
	v_pk_mul_f32 v[14:15], v[14:15], v[130:131] op_sel_hi:[1,0]
	v_pk_mul_f32 v[12:13], v[12:13], v[130:131] op_sel_hi:[1,0]
	v_pk_mul_f32 v[10:11], v[10:11], v[130:131] op_sel_hi:[1,0]
	v_pk_mul_f32 v[8:9], v[8:9], v[130:131] op_sel_hi:[1,0]
	v_pk_mul_f32 v[6:7], v[6:7], v[130:131] op_sel_hi:[1,0]
	v_pk_mul_f32 v[4:5], v[4:5], v[130:131] op_sel_hi:[1,0]
	v_pk_mul_f32 v[2:3], v[2:3], v[130:131] op_sel_hi:[1,0]
	v_pk_mul_f32 v[0:1], v[0:1], v[130:131] op_sel_hi:[1,0]
	v_pk_mul_f32 v[62:63], v[62:63], v[130:131] op_sel_hi:[1,0]
	v_pk_mul_f32 v[60:61], v[60:61], v[130:131] op_sel_hi:[1,0]
	v_pk_mul_f32 v[58:59], v[58:59], v[130:131] op_sel_hi:[1,0]
	v_pk_mul_f32 v[56:57], v[56:57], v[130:131] op_sel_hi:[1,0]
	v_pk_mul_f32 v[54:55], v[54:55], v[130:131] op_sel_hi:[1,0]
	v_pk_mul_f32 v[52:53], v[52:53], v[130:131] op_sel_hi:[1,0]
	v_pk_mul_f32 v[50:51], v[50:51], v[130:131] op_sel_hi:[1,0]
	v_pk_mul_f32 v[48:49], v[48:49], v[130:131] op_sel_hi:[1,0]
	v_pk_mul_f32 v[46:47], v[46:47], v[130:131] op_sel_hi:[1,0]
	v_pk_mul_f32 v[44:45], v[44:45], v[130:131] op_sel_hi:[1,0]
	v_pk_mul_f32 v[42:43], v[42:43], v[130:131] op_sel_hi:[1,0]
	v_pk_mul_f32 v[40:41], v[40:41], v[130:131] op_sel_hi:[1,0]
	v_pk_mul_f32 v[38:39], v[38:39], v[130:131] op_sel_hi:[1,0]
	v_pk_mul_f32 v[36:37], v[36:37], v[130:131] op_sel_hi:[1,0]
	v_pk_mul_f32 v[34:35], v[34:35], v[130:131] op_sel_hi:[1,0]
	v_pk_mul_f32 v[32:33], v[32:33], v[130:131] op_sel_hi:[1,0]
	v_pk_mul_f32 v[30:31], v[30:31], v[130:131] op_sel_hi:[1,0]
	v_pk_mul_f32 v[28:29], v[28:29], v[130:131] op_sel_hi:[1,0]
	v_pk_mul_f32 v[26:27], v[26:27], v[130:131] op_sel_hi:[1,0]
	v_pk_mul_f32 v[24:25], v[24:25], v[130:131] op_sel_hi:[1,0]
	v_pk_mul_f32 v[22:23], v[22:23], v[130:131] op_sel_hi:[1,0]
	v_pk_mul_f32 v[20:21], v[20:21], v[130:131] op_sel_hi:[1,0]
	v_pk_mul_f32 v[18:19], v[18:19], v[130:131] op_sel_hi:[1,0]
	v_pk_mul_f32 v[16:17], v[16:17], v[130:131] op_sel_hi:[1,0]
	v_mul_f32_e32 v160, v160, v130
	v_pk_add_f32 v[66:67], v[66:67], v[128:129] op_sel_hi:[1,0] neg_lo:[0,1] neg_hi:[0,1]
	v_pk_add_f32 v[84:85], v[84:85], v[128:129] op_sel_hi:[1,0] neg_lo:[0,1] neg_hi:[0,1]
	v_pk_add_f32 v[68:69], v[68:69], v[128:129] op_sel_hi:[1,0] neg_lo:[0,1] neg_hi:[0,1]
	v_pk_add_f32 v[86:87], v[86:87], v[128:129] op_sel_hi:[1,0] neg_lo:[0,1] neg_hi:[0,1]
	v_pk_add_f32 v[70:71], v[70:71], v[128:129] op_sel_hi:[1,0] neg_lo:[0,1] neg_hi:[0,1]
	v_pk_add_f32 v[88:89], v[88:89], v[128:129] op_sel_hi:[1,0] neg_lo:[0,1] neg_hi:[0,1]
	v_pk_add_f32 v[72:73], v[72:73], v[128:129] op_sel_hi:[1,0] neg_lo:[0,1] neg_hi:[0,1]
	v_pk_add_f32 v[90:91], v[90:91], v[128:129] op_sel_hi:[1,0] neg_lo:[0,1] neg_hi:[0,1]
	v_pk_add_f32 v[74:75], v[74:75], v[128:129] op_sel_hi:[1,0] neg_lo:[0,1] neg_hi:[0,1]
	v_pk_add_f32 v[92:93], v[92:93], v[128:129] op_sel_hi:[1,0] neg_lo:[0,1] neg_hi:[0,1]
	v_pk_add_f32 v[76:77], v[76:77], v[128:129] op_sel_hi:[1,0] neg_lo:[0,1] neg_hi:[0,1]
	v_pk_add_f32 v[94:95], v[94:95], v[128:129] op_sel_hi:[1,0] neg_lo:[0,1] neg_hi:[0,1]
	v_pk_add_f32 v[78:79], v[78:79], v[128:129] op_sel_hi:[1,0] neg_lo:[0,1] neg_hi:[0,1]
	s_branch .LBB0_822
